# K-loop back edge: loop-control SALU block hoisted above the iteration's final barrier (6 GEMM loops)
# baseline (speedup 1.0000x reference)
; #define PG8_STAGE(bufoff, gbase, voff) do { _Pragma("unroll") for (int _i = 0; _i < 2; ++_i) \
;         __builtin_amdgcn_global_load_lds((const unsigned*)((const char*)(gbase) + (voff)[_i]), (PG8_LAS unsigned*)(lds + (bufoff) + ldsw + _i * 8192), 16, 0, 0); } while (0)
; #define PG8_LDA(dst, b, h) do { _Pragma("unroll") for (int m = 0; m < 4; ++m) _Pragma("unroll") for (int k = 0; k < 2; ++k) dst[m][k] = *(const PG8_LAS bf16x8*)(lds + PG8_SA(b, h) + aoff + m * 2048 + k * 1024); } while (0)
; #define PG8_LDB(dst, b, h) do { _Pragma("unroll") for (int n = 0; n < 2; ++n) _Pragma("unroll") for (int k = 0; k < 2; ++k) dst[n][k] = *(const PG8_LAS bf16x8*)(lds + PG8_SB(b, h) + boff + n * 2048 + k * 1024); } while (0)
; #define PG8_MMA(ai, bj, At, Bt) do { __builtin_amdgcn_s_setprio(1); _Pragma("unroll") for (int m = 0; m < 4; ++m) _Pragma("unroll") for (int n = 0; n < 2; ++n) _Pragma("unroll") for (int k = 0; k < 2; ++k) \
;         acc[ai][bj][m][n] = __builtin_amdgcn_mfma_f32_16x16x32_bf16(Bt[n][k], At[m][k], acc[ai][bj][m][n], 0, 0, 0); __builtin_amdgcn_s_setprio(0); } while (0)
; #define PG8_WAIT_V(n) asm volatile("s_waitcnt vmcnt(" #n ")" ::: "memory")
; #define PG8_WAIT_L(n) asm volatile("s_waitcnt lgkmcnt(" #n ")" ::: "memory")
; template <class Epi, class Sched, bool ALIGN_EPI = false, bool SP2 = false>
; __device__ __forceinline__ void gemm_phase(PG8_LAS unsigned char* lds, const Gemm g, const Sched& S, const Epi& E) {
;     ...
;             const bool last = (t == nt - 2);
;             const char* a1 = cA + (size_t)(t + 1) * kstep;
;             const char* a2 = last ? nA : cA + (size_t)(t + 2) * kstep; const char* b2 = last ? nB : cB + (size_t)(t + 2) * kstep;
;             const char* a3 = a2 + kstep; const char* b3 = b2 + kstep;
;             if (last && has_next) S.a_ready(nxt);
;             if constexpr (SP2) {
;             PG8_LDB(B0, 0, 0); PG8_LDB(B1, 0, 1); PG8_SCHED; PG8_LDA(At, 0, 0); PG8_STAGE(PG8_SA(1, 1), a1 + hstepA, voffA);
;             PG8_WAIT_V(8); PG8_WAIT_L(0); PG8_BAR; PG8_MMA(0, 0, At, B0); PG8_MMA(0, 1, At, B1); PG8_BAR; PG8_SCHED;
;             PG8_LDA(At, 0, 1); PG8_STAGE(PG8_SB(0, 0), b2, voffB); PG8_STAGE(PG8_SB(0, 1), b2 + hstepB, voffB); PG8_STAGE(PG8_SA(0, 0), a2, voffA);
;             PG8_WAIT_V(8); PG8_WAIT_L(0); PG8_BAR; PG8_MMA(1, 0, At, B0); PG8_MMA(1, 1, At, B1); PG8_BAR; PG8_SCHED;
.LBB0_288:
	ds_read_b128 v[144:147], v159
	ds_read_b128 v[148:151], v159 offset:1024
	ds_read_b128 v[152:155], v159 offset:2048
	ds_read_b128 v[168:171], v159 offset:3072
	ds_read_b128 v[172:175], v160
	ds_read_b128 v[176:179], v160 offset:1024
	ds_read_b128 v[180:183], v160 offset:2048
	ds_read_b128 v[184:187], v160 offset:3072
	s_add_u32 s4, s36, 0xfff80080
	s_addc_u32 s5, s37, -1
	s_cmp_eq_u32 s59, 28
	s_cselect_b32 s41, s9, s5
	s_cselect_b32 s40, s11, s4
	s_cselect_b32 s39, s27, s51
	s_cselect_b32 s38, s29, s50
	v_lshl_add_u64 v[156:157], s[36:37], 0, v[136:137]
	s_add_i32 m0, s25, 0xc000
	ds_read_b128 v[188:191], v161
	ds_read_b128 v[192:195], v161 offset:1024
	ds_read_b128 v[196:199], v161 offset:2048
	ds_read_b128 v[200:203], v161 offset:3072
	ds_read_b128 v[204:207], v161 offset:4096
	ds_read_b128 v[208:211], v161 offset:5120
	ds_read_b128 v[212:215], v161 offset:6144
	ds_read_b128 v[216:219], v161 offset:7168
	global_load_lds_dwordx4 v[156:157], off
	v_lshl_add_u64 v[156:157], s[36:37], 0, v[138:139]
	s_add_i32 m0, s25, 0xe000
	s_nop 0
	global_load_lds_dwordx4 v[156:157], off
	s_waitcnt vmcnt(8)
	s_waitcnt lgkmcnt(0)
	s_barrier
	s_setprio 1
	v_mfma_f32_16x16x32_bf16 v[124:127], v[144:147], v[188:191], v[124:127]
	v_mfma_f32_16x16x32_bf16 v[120:123], v[152:155], v[188:191], v[120:123]
	v_mfma_f32_16x16x32_bf16 v[108:111], v[144:147], v[196:199], v[108:111]
	v_mfma_f32_16x16x32_bf16 v[104:107], v[152:155], v[196:199], v[104:107]
	v_mfma_f32_16x16x32_bf16 v[92:95], v[144:147], v[204:207], v[92:95]
	v_mfma_f32_16x16x32_bf16 v[88:91], v[152:155], v[204:207], v[88:91]
	v_mfma_f32_16x16x32_bf16 v[76:79], v[144:147], v[212:215], v[76:79]
	v_mfma_f32_16x16x32_bf16 v[72:75], v[152:155], v[212:215], v[72:75]
	v_mfma_f32_16x16x32_bf16 v[124:127], v[148:151], v[192:195], v[124:127]
	v_mfma_f32_16x16x32_bf16 v[120:123], v[168:171], v[192:195], v[120:123]
	v_mfma_f32_16x16x32_bf16 v[108:111], v[148:151], v[200:203], v[108:111]
	v_mfma_f32_16x16x32_bf16 v[104:107], v[168:171], v[200:203], v[104:107]
	v_mfma_f32_16x16x32_bf16 v[92:95], v[148:151], v[208:211], v[92:95]
	v_mfma_f32_16x16x32_bf16 v[88:91], v[168:171], v[208:211], v[88:91]
	v_mfma_f32_16x16x32_bf16 v[76:79], v[148:151], v[216:219], v[76:79]
	v_mfma_f32_16x16x32_bf16 v[72:75], v[168:171], v[216:219], v[72:75]
	v_mfma_f32_16x16x32_bf16 v[116:119], v[172:175], v[188:191], v[116:119]
	v_mfma_f32_16x16x32_bf16 v[112:115], v[180:183], v[188:191], v[112:115]
	v_mfma_f32_16x16x32_bf16 v[100:103], v[172:175], v[196:199], v[100:103]
	v_mfma_f32_16x16x32_bf16 v[96:99], v[180:183], v[196:199], v[96:99]
	v_mfma_f32_16x16x32_bf16 v[84:87], v[172:175], v[204:207], v[84:87]
	v_mfma_f32_16x16x32_bf16 v[80:83], v[180:183], v[204:207], v[80:83]
	v_mfma_f32_16x16x32_bf16 v[68:71], v[172:175], v[212:215], v[68:71]
	v_mfma_f32_16x16x32_bf16 v[64:67], v[180:183], v[212:215], v[64:67]
	v_mfma_f32_16x16x32_bf16 v[116:119], v[176:179], v[192:195], v[116:119]
	v_mfma_f32_16x16x32_bf16 v[112:115], v[184:187], v[192:195], v[112:115]
	v_mfma_f32_16x16x32_bf16 v[100:103], v[176:179], v[200:203], v[100:103]
	v_mfma_f32_16x16x32_bf16 v[96:99], v[184:187], v[200:203], v[96:99]
	v_mfma_f32_16x16x32_bf16 v[84:87], v[176:179], v[208:211], v[84:87]
	v_mfma_f32_16x16x32_bf16 v[80:83], v[184:187], v[208:211], v[80:83]
	v_mfma_f32_16x16x32_bf16 v[68:71], v[176:179], v[216:219], v[68:71]
	v_mfma_f32_16x16x32_bf16 v[64:67], v[184:187], v[216:219], v[64:67]
	s_setprio 0
	s_barrier
	s_add_i32 s4, s55, s47
	v_lshl_add_u64 v[156:157], s[38:39], 0, v[130:131]
	s_mov_b32 m0, s4
	ds_read_b128 v[188:191], v161 offset:16384
	ds_read_b128 v[192:195], v161 offset:17408
	ds_read_b128 v[196:199], v161 offset:18432
	ds_read_b128 v[200:203], v161 offset:19456
	ds_read_b128 v[204:207], v161 offset:20480
	ds_read_b128 v[208:211], v161 offset:21504
	ds_read_b128 v[212:215], v161 offset:22528
	ds_read_b128 v[216:219], v161 offset:23552
	global_load_lds_dwordx4 v[156:157], off
	s_add_i32 m0, s4, 0x2000
	s_add_u32 s60, s38, 0x80000
	v_lshl_add_u64 v[164:165], s[38:39], 0, v[134:135]
	s_addc_u32 s61, s39, 0
	s_add_i32 s4, s56, s47
	global_load_lds_dwordx4 v[164:165], off
	v_lshl_add_u64 v[220:221], s[60:61], 0, v[130:131]
	s_mov_b32 m0, s4
	v_lshl_add_u64 v[222:223], s[40:41], 0, v[132:133]
	global_load_lds_dwordx4 v[220:221], off
	v_lshl_add_u64 v[220:221], s[60:61], 0, v[134:135]
	s_add_i32 m0, s4, 0x2000
	s_nop 0
	global_load_lds_dwordx4 v[220:221], off
	v_lshl_add_u64 v[220:221], s[40:41], 0, v[128:129]
	s_mov_b32 m0, s25
	s_nop 0
	global_load_lds_dwordx4 v[220:221], off
	s_mov_b32 m0, s33
	s_nop 0
	global_load_lds_dwordx4 v[222:223], off
	s_waitcnt vmcnt(8)
	s_waitcnt lgkmcnt(0)
	s_barrier
; #define PG8_STAGE(bufoff, gbase, voff) do { _Pragma("unroll") for (int _i = 0; _i < 2; ++_i) \
;         __builtin_amdgcn_global_load_lds((const unsigned*)((const char*)(gbase) + (voff)[_i]), (PG8_LAS unsigned*)(lds + (bufoff) + ldsw + _i * 8192), 16, 0, 0); } while (0)
; #define PG8_LDA(dst, b, h) do { _Pragma("unroll") for (int m = 0; m < 4; ++m) _Pragma("unroll") for (int k = 0; k < 2; ++k) dst[m][k] = *(const PG8_LAS bf16x8*)(lds + PG8_SA(b, h) + aoff + m * 2048 + k * 1024); } while (0)
; #define PG8_LDB(dst, b, h) do { _Pragma("unroll") for (int n = 0; n < 2; ++n) _Pragma("unroll") for (int k = 0; k < 2; ++k) dst[n][k] = *(const PG8_LAS bf16x8*)(lds + PG8_SB(b, h) + boff + n * 2048 + k * 1024); } while (0)
; #define PG8_MMA(ai, bj, At, Bt) do { __builtin_amdgcn_s_setprio(1); _Pragma("unroll") for (int m = 0; m < 4; ++m) _Pragma("unroll") for (int n = 0; n < 2; ++n) _Pragma("unroll") for (int k = 0; k < 2; ++k) \
;         acc[ai][bj][m][n] = __builtin_amdgcn_mfma_f32_16x16x32_bf16(Bt[n][k], At[m][k], acc[ai][bj][m][n], 0, 0, 0); __builtin_amdgcn_s_setprio(0); } while (0)
; #define PG8_WAIT_V(n) asm volatile("s_waitcnt vmcnt(" #n ")" ::: "memory")
; #define PG8_WAIT_L(n) asm volatile("s_waitcnt lgkmcnt(" #n ")" ::: "memory")
; #define PG8_BAR __builtin_amdgcn_s_barrier()
; #define PG8_SCHED __builtin_amdgcn_sched_barrier(0)
; template <class Epi, class Sched, bool ALIGN_EPI = false, bool SP2 = false>
; __device__ __forceinline__ void gemm_phase(PG8_LAS unsigned char* lds, const Gemm g, const Sched& S, const Epi& E) {
;     ...
;             PG8_WAIT_V(8); PG8_WAIT_L(0); PG8_BAR; PG8_MMA(1, 0, At, B0); PG8_MMA(1, 1, At, B1); PG8_BAR; PG8_SCHED;
;             PG8_LDB(B0, 1, 0); PG8_LDB(B1, 1, 1); PG8_SCHED; PG8_LDA(At, 1, 0); PG8_STAGE(PG8_SA(0, 1), a2 + hstepA, voffA);
;             PG8_WAIT_V(8); PG8_WAIT_L(0); PG8_BAR; PG8_MMA(0, 0, At, B0); PG8_MMA(0, 1, At, B1); PG8_BAR; PG8_SCHED;
	s_setprio 1
	v_mfma_f32_16x16x32_bf16 v[60:63], v[144:147], v[188:191], v[60:63]
	v_mfma_f32_16x16x32_bf16 v[56:59], v[152:155], v[188:191], v[56:59]
	v_mfma_f32_16x16x32_bf16 v[44:47], v[144:147], v[196:199], v[44:47]
	v_mfma_f32_16x16x32_bf16 v[40:43], v[152:155], v[196:199], v[40:43]
	v_mfma_f32_16x16x32_bf16 v[28:31], v[144:147], v[204:207], v[28:31]
	v_mfma_f32_16x16x32_bf16 v[24:27], v[152:155], v[204:207], v[24:27]
	v_mfma_f32_16x16x32_bf16 v[12:15], v[144:147], v[212:215], v[12:15]
	v_mfma_f32_16x16x32_bf16 v[8:11], v[152:155], v[212:215], v[8:11]
	v_mfma_f32_16x16x32_bf16 v[60:63], v[148:151], v[192:195], v[60:63]
	v_mfma_f32_16x16x32_bf16 v[56:59], v[168:171], v[192:195], v[56:59]
	v_mfma_f32_16x16x32_bf16 v[44:47], v[148:151], v[200:203], v[44:47]
	v_mfma_f32_16x16x32_bf16 v[40:43], v[168:171], v[200:203], v[40:43]
	v_mfma_f32_16x16x32_bf16 v[28:31], v[148:151], v[208:211], v[28:31]
	v_mfma_f32_16x16x32_bf16 v[24:27], v[168:171], v[208:211], v[24:27]
	v_mfma_f32_16x16x32_bf16 v[12:15], v[148:151], v[216:219], v[12:15]
	v_mfma_f32_16x16x32_bf16 v[8:11], v[168:171], v[216:219], v[8:11]
	v_mfma_f32_16x16x32_bf16 v[52:55], v[172:175], v[188:191], v[52:55]
	v_mfma_f32_16x16x32_bf16 v[48:51], v[180:183], v[188:191], v[48:51]
	v_mfma_f32_16x16x32_bf16 v[36:39], v[172:175], v[196:199], v[36:39]
	v_mfma_f32_16x16x32_bf16 v[32:35], v[180:183], v[196:199], v[32:35]
	v_mfma_f32_16x16x32_bf16 v[20:23], v[172:175], v[204:207], v[20:23]
	v_mfma_f32_16x16x32_bf16 v[16:19], v[180:183], v[204:207], v[16:19]
	v_mfma_f32_16x16x32_bf16 v[4:7], v[172:175], v[212:215], v[4:7]
	v_mfma_f32_16x16x32_bf16 v[0:3], v[180:183], v[212:215], v[0:3]
	v_mfma_f32_16x16x32_bf16 v[52:55], v[176:179], v[192:195], v[52:55]
	v_mfma_f32_16x16x32_bf16 v[48:51], v[184:187], v[192:195], v[48:51]
	v_mfma_f32_16x16x32_bf16 v[36:39], v[176:179], v[200:203], v[36:39]
	v_mfma_f32_16x16x32_bf16 v[32:35], v[184:187], v[200:203], v[32:35]
	v_mfma_f32_16x16x32_bf16 v[20:23], v[176:179], v[208:211], v[20:23]
	v_mfma_f32_16x16x32_bf16 v[16:19], v[184:187], v[208:211], v[16:19]
	v_mfma_f32_16x16x32_bf16 v[4:7], v[176:179], v[216:219], v[4:7]
	v_mfma_f32_16x16x32_bf16 v[0:3], v[184:187], v[216:219], v[0:3]
	s_setprio 0
	s_barrier
	s_add_i32 s4, 0, 0x18000
	v_add_u32_e32 v163, s4, v158
	s_add_i32 s5, 0, 0x1c000
	ds_read_b128 v[144:147], v163
	ds_read_b128 v[148:151], v163 offset:1024
	ds_read_b128 v[152:155], v163 offset:2048
	ds_read_b128 v[168:171], v163 offset:3072
	v_add_u32_e32 v163, s5, v158
	ds_read_b128 v[172:175], v163
	ds_read_b128 v[176:179], v163 offset:1024
	ds_read_b128 v[180:183], v163 offset:2048
	ds_read_b128 v[184:187], v163 offset:3072
	s_add_u32 s40, s40, 0x80000
	s_addc_u32 s41, s41, 0
	s_mov_b32 m0, s44
	v_lshl_add_u64 v[224:225], s[40:41], 0, v[128:129]
	ds_read_b128 v[188:191], v161 offset:32768
	ds_read_b128 v[192:195], v161 offset:33792
	ds_read_b128 v[196:199], v161 offset:34816
	ds_read_b128 v[200:203], v161 offset:35840
	ds_read_b128 v[204:207], v161 offset:36864
	ds_read_b128 v[208:211], v161 offset:37888
	ds_read_b128 v[212:215], v161 offset:38912
	ds_read_b128 v[216:219], v161 offset:39936
	global_load_lds_dwordx4 v[224:225], off
	v_lshl_add_u64 v[224:225], s[40:41], 0, v[132:133]
	s_mov_b32 m0, s45
	s_nop 0
	global_load_lds_dwordx4 v[224:225], off
	s_waitcnt vmcnt(8)
	s_waitcnt lgkmcnt(0)
	s_barrier
	s_setprio 1
	v_mfma_f32_16x16x32_bf16 v[124:127], v[144:147], v[188:191], v[124:127]
	v_mfma_f32_16x16x32_bf16 v[120:123], v[152:155], v[188:191], v[120:123]
	v_mfma_f32_16x16x32_bf16 v[108:111], v[144:147], v[196:199], v[108:111]
	v_mfma_f32_16x16x32_bf16 v[104:107], v[152:155], v[196:199], v[104:107]
	v_mfma_f32_16x16x32_bf16 v[92:95], v[144:147], v[204:207], v[92:95]
	v_mfma_f32_16x16x32_bf16 v[88:91], v[152:155], v[204:207], v[88:91]
	v_mfma_f32_16x16x32_bf16 v[76:79], v[144:147], v[212:215], v[76:79]
	v_mfma_f32_16x16x32_bf16 v[72:75], v[152:155], v[212:215], v[72:75]
	v_mfma_f32_16x16x32_bf16 v[124:127], v[148:151], v[192:195], v[124:127]
	v_mfma_f32_16x16x32_bf16 v[120:123], v[168:171], v[192:195], v[120:123]
	v_mfma_f32_16x16x32_bf16 v[108:111], v[148:151], v[200:203], v[108:111]
	v_mfma_f32_16x16x32_bf16 v[104:107], v[168:171], v[200:203], v[104:107]
	v_mfma_f32_16x16x32_bf16 v[92:95], v[148:151], v[208:211], v[92:95]
	v_mfma_f32_16x16x32_bf16 v[88:91], v[168:171], v[208:211], v[88:91]
	v_mfma_f32_16x16x32_bf16 v[76:79], v[148:151], v[216:219], v[76:79]
	v_mfma_f32_16x16x32_bf16 v[72:75], v[168:171], v[216:219], v[72:75]
	v_mfma_f32_16x16x32_bf16 v[116:119], v[172:175], v[188:191], v[116:119]
	v_mfma_f32_16x16x32_bf16 v[112:115], v[180:183], v[188:191], v[112:115]
	v_mfma_f32_16x16x32_bf16 v[100:103], v[172:175], v[196:199], v[100:103]
	v_mfma_f32_16x16x32_bf16 v[96:99], v[180:183], v[196:199], v[96:99]
	v_mfma_f32_16x16x32_bf16 v[84:87], v[172:175], v[204:207], v[84:87]
	v_mfma_f32_16x16x32_bf16 v[80:83], v[180:183], v[204:207], v[80:83]
	v_mfma_f32_16x16x32_bf16 v[68:71], v[172:175], v[212:215], v[68:71]
	v_mfma_f32_16x16x32_bf16 v[64:67], v[180:183], v[212:215], v[64:67]
	v_mfma_f32_16x16x32_bf16 v[116:119], v[176:179], v[192:195], v[116:119]
	v_mfma_f32_16x16x32_bf16 v[112:115], v[184:187], v[192:195], v[112:115]
	v_mfma_f32_16x16x32_bf16 v[100:103], v[176:179], v[200:203], v[100:103]
	v_mfma_f32_16x16x32_bf16 v[96:99], v[184:187], v[200:203], v[96:99]
	v_mfma_f32_16x16x32_bf16 v[84:87], v[176:179], v[208:211], v[84:87]
	v_mfma_f32_16x16x32_bf16 v[80:83], v[184:187], v[208:211], v[80:83]
	v_mfma_f32_16x16x32_bf16 v[68:71], v[176:179], v[216:219], v[68:71]
	v_mfma_f32_16x16x32_bf16 v[64:67], v[184:187], v[216:219], v[64:67]
	s_setprio 0
	s_barrier
; #define PG8_STAGE(bufoff, gbase, voff) do { _Pragma("unroll") for (int _i = 0; _i < 2; ++_i) \
;         __builtin_amdgcn_global_load_lds((const unsigned*)((const char*)(gbase) + (voff)[_i]), (PG8_LAS unsigned*)(lds + (bufoff) + ldsw + _i * 8192), 16, 0, 0); } while (0)
; #define PG8_LDA(dst, b, h) do { _Pragma("unroll") for (int m = 0; m < 4; ++m) _Pragma("unroll") for (int k = 0; k < 2; ++k) dst[m][k] = *(const PG8_LAS bf16x8*)(lds + PG8_SA(b, h) + aoff + m * 2048 + k * 1024); } while (0)
; #define PG8_MMA(ai, bj, At, Bt) do { __builtin_amdgcn_s_setprio(1); _Pragma("unroll") for (int m = 0; m < 4; ++m) _Pragma("unroll") for (int n = 0; n < 2; ++n) _Pragma("unroll") for (int k = 0; k < 2; ++k) \
;         acc[ai][bj][m][n] = __builtin_amdgcn_mfma_f32_16x16x32_bf16(Bt[n][k], At[m][k], acc[ai][bj][m][n], 0, 0, 0); __builtin_amdgcn_s_setprio(0); } while (0)
; #define PG8_WAIT_V(n) asm volatile("s_waitcnt vmcnt(" #n ")" ::: "memory")
; #define PG8_WAIT_L(n) asm volatile("s_waitcnt lgkmcnt(" #n ")" ::: "memory")
; #define PG8_BAR __builtin_amdgcn_s_barrier()
; #define PG8_SCHED __builtin_amdgcn_sched_barrier(0)
; template <class Epi, class Sched, bool ALIGN_EPI = false, bool SP2 = false>
; __device__ __forceinline__ void gemm_phase(PG8_LAS unsigned char* lds, const Gemm g, const Sched& S, const Epi& E) {
;     ...
;         for (int t = 0; t < nt; t += 2) {
;     ...
;             PG8_LDA(At, 1, 1); PG8_STAGE(PG8_SB(1, 0), b3, voffB); PG8_STAGE(PG8_SB(1, 1), b3 + hstepB, voffB); PG8_STAGE(PG8_SA(1, 0), a3, voffA);
;             PG8_WAIT_V(8); PG8_WAIT_L(0); PG8_BAR; PG8_MMA(1, 0, At, B0); PG8_MMA(1, 1, At, B1); PG8_BAR; PG8_SCHED;
	s_add_i32 s4, s4, s47
	v_lshl_add_u64 v[156:157], v[156:157], 0, s[22:23]
	s_mov_b32 m0, s4
	ds_read_b128 v[188:191], v161 offset:49152
	ds_read_b128 v[192:195], v161 offset:50176
	ds_read_b128 v[196:199], v161 offset:51200
	ds_read_b128 v[200:203], v161 offset:52224
	ds_read_b128 v[204:207], v161 offset:53248
	ds_read_b128 v[208:211], v161 offset:54272
	ds_read_b128 v[212:215], v161 offset:55296
	ds_read_b128 v[216:219], v161 offset:56320
	global_load_lds_dwordx4 v[156:157], off
	s_add_i32 m0, s4, 0x2000
	s_add_u32 s38, s38, 0x80080
	v_lshl_add_u64 v[156:157], v[164:165], 0, s[22:23]
	s_addc_u32 s39, s39, 0
	s_add_i32 s4, s5, s47
	global_load_lds_dwordx4 v[156:157], off
	v_lshl_add_u64 v[156:157], s[38:39], 0, v[130:131]
	s_mov_b32 m0, s4
	s_nop 0
	global_load_lds_dwordx4 v[156:157], off
	v_lshl_add_u64 v[156:157], s[38:39], 0, v[134:135]
	s_add_i32 m0, s4, 0x2000
	s_nop 0
	global_load_lds_dwordx4 v[156:157], off
	v_lshl_add_u64 v[156:157], v[220:221], 0, s[22:23]
	s_mov_b32 m0, s46
	s_nop 0
	global_load_lds_dwordx4 v[156:157], off
	v_lshl_add_u64 v[156:157], v[222:223], 0, s[22:23]
	s_mov_b32 m0, s53
	s_nop 0
	global_load_lds_dwordx4 v[156:157], off
	s_waitcnt vmcnt(8)
	s_waitcnt lgkmcnt(0)
	s_barrier
	s_setprio 1
	v_mfma_f32_16x16x32_bf16 v[60:63], v[144:147], v[188:191], v[60:63]
	v_mfma_f32_16x16x32_bf16 v[56:59], v[152:155], v[188:191], v[56:59]
	v_mfma_f32_16x16x32_bf16 v[44:47], v[144:147], v[196:199], v[44:47]
	v_mfma_f32_16x16x32_bf16 v[40:43], v[152:155], v[196:199], v[40:43]
	v_mfma_f32_16x16x32_bf16 v[28:31], v[144:147], v[204:207], v[28:31]
	v_mfma_f32_16x16x32_bf16 v[24:27], v[152:155], v[204:207], v[24:27]
	v_mfma_f32_16x16x32_bf16 v[12:15], v[144:147], v[212:215], v[12:15]
	v_mfma_f32_16x16x32_bf16 v[8:11], v[152:155], v[212:215], v[8:11]
	v_mfma_f32_16x16x32_bf16 v[60:63], v[148:151], v[192:195], v[60:63]
	v_mfma_f32_16x16x32_bf16 v[56:59], v[168:171], v[192:195], v[56:59]
	v_mfma_f32_16x16x32_bf16 v[44:47], v[148:151], v[200:203], v[44:47]
	v_mfma_f32_16x16x32_bf16 v[40:43], v[168:171], v[200:203], v[40:43]
	v_mfma_f32_16x16x32_bf16 v[28:31], v[148:151], v[208:211], v[28:31]
	v_mfma_f32_16x16x32_bf16 v[24:27], v[168:171], v[208:211], v[24:27]
	v_mfma_f32_16x16x32_bf16 v[12:15], v[148:151], v[216:219], v[12:15]
	v_mfma_f32_16x16x32_bf16 v[8:11], v[168:171], v[216:219], v[8:11]
	v_mfma_f32_16x16x32_bf16 v[52:55], v[172:175], v[188:191], v[52:55]
	v_mfma_f32_16x16x32_bf16 v[48:51], v[180:183], v[188:191], v[48:51]
	v_mfma_f32_16x16x32_bf16 v[36:39], v[172:175], v[196:199], v[36:39]
	v_mfma_f32_16x16x32_bf16 v[32:35], v[180:183], v[196:199], v[32:35]
	v_mfma_f32_16x16x32_bf16 v[20:23], v[172:175], v[204:207], v[20:23]
	v_mfma_f32_16x16x32_bf16 v[16:19], v[180:183], v[204:207], v[16:19]
	v_mfma_f32_16x16x32_bf16 v[4:7], v[172:175], v[212:215], v[4:7]
	v_mfma_f32_16x16x32_bf16 v[0:3], v[180:183], v[212:215], v[0:3]
	v_mfma_f32_16x16x32_bf16 v[52:55], v[176:179], v[192:195], v[52:55]
	v_mfma_f32_16x16x32_bf16 v[48:51], v[184:187], v[192:195], v[48:51]
	v_mfma_f32_16x16x32_bf16 v[36:39], v[176:179], v[200:203], v[36:39]
	v_mfma_f32_16x16x32_bf16 v[32:35], v[184:187], v[200:203], v[32:35]
	v_mfma_f32_16x16x32_bf16 v[20:23], v[176:179], v[208:211], v[20:23]
	v_mfma_f32_16x16x32_bf16 v[16:19], v[184:187], v[208:211], v[16:19]
	v_mfma_f32_16x16x32_bf16 v[4:7], v[176:179], v[216:219], v[4:7]
	v_mfma_f32_16x16x32_bf16 v[0:3], v[184:187], v[216:219], v[0:3]
	s_add_i32 s59, s59, 2
	s_add_u32 s36, s36, 0x100
	s_addc_u32 s37, s37, 0
	s_add_u32 s50, s50, 0x100
	s_addc_u32 s51, s51, 0
	s_cmp_gt_u32 s59, 29
	s_setprio 0
	s_barrier
	s_cbranch_scc0 .LBB0_288
	s_and_b64 vcc, exec, s[48:49]
	s_cbranch_vccz .LBB0_291
	s_barrier

; #define PG8_STAGE(bufoff, gbase, voff) do { _Pragma("unroll") for (int _i = 0; _i < 2; ++_i) \
;         __builtin_amdgcn_global_load_lds((const unsigned*)((const char*)(gbase) + (voff)[_i]), (PG8_LAS unsigned*)(lds + (bufoff) + ldsw + _i * 8192), 16, 0, 0); } while (0)
; #define PG8_LDA(dst, b, h) do { _Pragma("unroll") for (int m = 0; m < 4; ++m) _Pragma("unroll") for (int k = 0; k < 2; ++k) dst[m][k] = *(const PG8_LAS bf16x8*)(lds + PG8_SA(b, h) + aoff + m * 2048 + k * 1024); } while (0)
; #define PG8_LDB(dst, b, h) do { _Pragma("unroll") for (int n = 0; n < 2; ++n) _Pragma("unroll") for (int k = 0; k < 2; ++k) dst[n][k] = *(const PG8_LAS bf16x8*)(lds + PG8_SB(b, h) + boff + n * 2048 + k * 1024); } while (0)
; #define PG8_MMA(ai, bj, At, Bt) do { __builtin_amdgcn_s_setprio(1); _Pragma("unroll") for (int m = 0; m < 4; ++m) _Pragma("unroll") for (int n = 0; n < 2; ++n) _Pragma("unroll") for (int k = 0; k < 2; ++k) \
;         acc[ai][bj][m][n] = __builtin_amdgcn_mfma_f32_16x16x32_bf16(Bt[n][k], At[m][k], acc[ai][bj][m][n], 0, 0, 0); __builtin_amdgcn_s_setprio(0); } while (0)
; #define PG8_WAIT_V(n) asm volatile("s_waitcnt vmcnt(" #n ")" ::: "memory")
; #define PG8_WAIT_L(n) asm volatile("s_waitcnt lgkmcnt(" #n ")" ::: "memory")
; template <class Epi, class Sched, bool ALIGN_EPI = false, bool SP2 = false>
; __device__ __forceinline__ void gemm_phase(PG8_LAS unsigned char* lds, const Gemm g, const Sched& S, const Epi& E) {
;     ...
;             const bool last = (t == nt - 2);
;             const char* a1 = cA + (size_t)(t + 1) * kstep;
;             const char* a2 = last ? nA : cA + (size_t)(t + 2) * kstep; const char* b2 = last ? nB : cB + (size_t)(t + 2) * kstep;
;             const char* a3 = a2 + kstep; const char* b3 = b2 + kstep;
;             if (last && has_next) S.a_ready(nxt);
;             if constexpr (SP2) {
;             PG8_LDB(B0, 0, 0); PG8_LDB(B1, 0, 1); PG8_SCHED; PG8_LDA(At, 0, 0); PG8_STAGE(PG8_SA(1, 1), a1 + hstepA, voffA);
;             PG8_WAIT_V(8); PG8_WAIT_L(0); PG8_BAR; PG8_MMA(0, 0, At, B0); PG8_MMA(0, 1, At, B1); PG8_BAR; PG8_SCHED;
;             PG8_LDA(At, 0, 1); PG8_STAGE(PG8_SB(0, 0), b2, voffB); PG8_STAGE(PG8_SB(0, 1), b2 + hstepB, voffB); PG8_STAGE(PG8_SA(0, 0), a2, voffA);
;             PG8_WAIT_V(8); PG8_WAIT_L(0); PG8_BAR; PG8_MMA(1, 0, At, B0); PG8_MMA(1, 1, At, B1); PG8_BAR; PG8_SCHED;
.LBB0_660:
	ds_read_b128 v[144:147], v149
	ds_read_b128 v[152:155], v149 offset:1024
	ds_read_b128 v[156:159], v149 offset:2048
	ds_read_b128 v[160:163], v149 offset:3072
	ds_read_b128 v[168:171], v150
	ds_read_b128 v[172:175], v150 offset:1024
	ds_read_b128 v[176:179], v150 offset:2048
	ds_read_b128 v[180:183], v150 offset:3072
	s_add_u32 s4, s30, 0xfff80080
	s_addc_u32 s5, s31, -1
	s_cmp_eq_u32 s56, 28
	s_cselect_b32 s37, s21, s5
	s_cselect_b32 s36, s29, s4
	s_cselect_b32 s35, s19, s55
	s_cselect_b32 s34, s53, s54
	v_lshl_add_u64 v[164:165], s[30:31], 0, v[136:137]
	s_add_i32 m0, s25, 0xc000
	ds_read_b128 v[184:187], v151
	ds_read_b128 v[188:191], v151 offset:1024
	ds_read_b128 v[192:195], v151 offset:2048
	ds_read_b128 v[196:199], v151 offset:3072
	ds_read_b128 v[200:203], v151 offset:4096
	ds_read_b128 v[204:207], v151 offset:5120
	ds_read_b128 v[208:211], v151 offset:6144
	ds_read_b128 v[212:215], v151 offset:7168
	global_load_lds_dwordx4 v[164:165], off
	v_lshl_add_u64 v[164:165], s[30:31], 0, v[138:139]
	s_add_i32 m0, s25, 0xe000
	s_nop 0
	global_load_lds_dwordx4 v[164:165], off
	s_waitcnt vmcnt(8)
	s_waitcnt lgkmcnt(0)
	s_barrier
	s_setprio 1
	v_mfma_f32_16x16x32_bf16 v[124:127], v[144:147], v[184:187], v[124:127]
	v_mfma_f32_16x16x32_bf16 v[120:123], v[156:159], v[184:187], v[120:123]
	v_mfma_f32_16x16x32_bf16 v[108:111], v[144:147], v[192:195], v[108:111]
	v_mfma_f32_16x16x32_bf16 v[104:107], v[156:159], v[192:195], v[104:107]
	v_mfma_f32_16x16x32_bf16 v[92:95], v[144:147], v[200:203], v[92:95]
	v_mfma_f32_16x16x32_bf16 v[88:91], v[156:159], v[200:203], v[88:91]
	v_mfma_f32_16x16x32_bf16 v[76:79], v[144:147], v[208:211], v[76:79]
	v_mfma_f32_16x16x32_bf16 v[72:75], v[156:159], v[208:211], v[72:75]
	v_mfma_f32_16x16x32_bf16 v[124:127], v[152:155], v[188:191], v[124:127]
	v_mfma_f32_16x16x32_bf16 v[120:123], v[160:163], v[188:191], v[120:123]
	v_mfma_f32_16x16x32_bf16 v[108:111], v[152:155], v[196:199], v[108:111]
	v_mfma_f32_16x16x32_bf16 v[104:107], v[160:163], v[196:199], v[104:107]
	v_mfma_f32_16x16x32_bf16 v[92:95], v[152:155], v[204:207], v[92:95]
	v_mfma_f32_16x16x32_bf16 v[88:91], v[160:163], v[204:207], v[88:91]
	v_mfma_f32_16x16x32_bf16 v[76:79], v[152:155], v[212:215], v[76:79]
	v_mfma_f32_16x16x32_bf16 v[72:75], v[160:163], v[212:215], v[72:75]
	v_mfma_f32_16x16x32_bf16 v[116:119], v[168:171], v[184:187], v[116:119]
	v_mfma_f32_16x16x32_bf16 v[112:115], v[176:179], v[184:187], v[112:115]
	v_mfma_f32_16x16x32_bf16 v[100:103], v[168:171], v[192:195], v[100:103]
	v_mfma_f32_16x16x32_bf16 v[96:99], v[176:179], v[192:195], v[96:99]
	v_mfma_f32_16x16x32_bf16 v[84:87], v[168:171], v[200:203], v[84:87]
	v_mfma_f32_16x16x32_bf16 v[80:83], v[176:179], v[200:203], v[80:83]
	v_mfma_f32_16x16x32_bf16 v[68:71], v[168:171], v[208:211], v[68:71]
	v_mfma_f32_16x16x32_bf16 v[64:67], v[176:179], v[208:211], v[64:67]
	v_mfma_f32_16x16x32_bf16 v[116:119], v[172:175], v[188:191], v[116:119]
	v_mfma_f32_16x16x32_bf16 v[112:115], v[180:183], v[188:191], v[112:115]
	v_mfma_f32_16x16x32_bf16 v[100:103], v[172:175], v[196:199], v[100:103]
	v_mfma_f32_16x16x32_bf16 v[96:99], v[180:183], v[196:199], v[96:99]
	v_mfma_f32_16x16x32_bf16 v[84:87], v[172:175], v[204:207], v[84:87]
	v_mfma_f32_16x16x32_bf16 v[80:83], v[180:183], v[204:207], v[80:83]
	v_mfma_f32_16x16x32_bf16 v[68:71], v[172:175], v[212:215], v[68:71]
	v_mfma_f32_16x16x32_bf16 v[64:67], v[180:183], v[212:215], v[64:67]
	s_setprio 0
	s_barrier
	s_add_i32 s4, s44, s47
	v_lshl_add_u64 v[164:165], s[34:35], 0, v[130:131]
	s_mov_b32 m0, s4
	ds_read_b128 v[184:187], v151 offset:16384
	ds_read_b128 v[188:191], v151 offset:17408
	ds_read_b128 v[192:195], v151 offset:18432
	ds_read_b128 v[196:199], v151 offset:19456
	ds_read_b128 v[200:203], v151 offset:20480
	ds_read_b128 v[204:207], v151 offset:21504
	ds_read_b128 v[208:211], v151 offset:22528
	ds_read_b128 v[212:215], v151 offset:23552
	global_load_lds_dwordx4 v[164:165], off
	s_add_i32 m0, s4, 0x2000
	s_add_u32 s58, s34, 0x80000
	v_lshl_add_u64 v[216:217], s[34:35], 0, v[134:135]
	s_addc_u32 s59, s35, 0
	s_add_i32 s4, s45, s47
	global_load_lds_dwordx4 v[216:217], off
	v_lshl_add_u64 v[218:219], s[58:59], 0, v[130:131]
	s_mov_b32 m0, s4
	v_lshl_add_u64 v[220:221], s[36:37], 0, v[132:133]
	global_load_lds_dwordx4 v[218:219], off
	v_lshl_add_u64 v[218:219], s[58:59], 0, v[134:135]
	s_add_i32 m0, s4, 0x2000
	s_nop 0
	global_load_lds_dwordx4 v[218:219], off
	v_lshl_add_u64 v[218:219], s[36:37], 0, v[128:129]
	s_mov_b32 m0, s25
	s_nop 0
	global_load_lds_dwordx4 v[218:219], off
	s_mov_b32 m0, s33
	s_nop 0
	global_load_lds_dwordx4 v[220:221], off
	s_waitcnt vmcnt(8)
	s_waitcnt lgkmcnt(0)
	s_barrier
; #define PG8_STAGE(bufoff, gbase, voff) do { _Pragma("unroll") for (int _i = 0; _i < 2; ++_i) \
;         __builtin_amdgcn_global_load_lds((const unsigned*)((const char*)(gbase) + (voff)[_i]), (PG8_LAS unsigned*)(lds + (bufoff) + ldsw + _i * 8192), 16, 0, 0); } while (0)
; #define PG8_LDA(dst, b, h) do { _Pragma("unroll") for (int m = 0; m < 4; ++m) _Pragma("unroll") for (int k = 0; k < 2; ++k) dst[m][k] = *(const PG8_LAS bf16x8*)(lds + PG8_SA(b, h) + aoff + m * 2048 + k * 1024); } while (0)
; #define PG8_LDB(dst, b, h) do { _Pragma("unroll") for (int n = 0; n < 2; ++n) _Pragma("unroll") for (int k = 0; k < 2; ++k) dst[n][k] = *(const PG8_LAS bf16x8*)(lds + PG8_SB(b, h) + boff + n * 2048 + k * 1024); } while (0)
; #define PG8_MMA(ai, bj, At, Bt) do { __builtin_amdgcn_s_setprio(1); _Pragma("unroll") for (int m = 0; m < 4; ++m) _Pragma("unroll") for (int n = 0; n < 2; ++n) _Pragma("unroll") for (int k = 0; k < 2; ++k) \
;         acc[ai][bj][m][n] = __builtin_amdgcn_mfma_f32_16x16x32_bf16(Bt[n][k], At[m][k], acc[ai][bj][m][n], 0, 0, 0); __builtin_amdgcn_s_setprio(0); } while (0)
; #define PG8_WAIT_V(n) asm volatile("s_waitcnt vmcnt(" #n ")" ::: "memory")
; #define PG8_WAIT_L(n) asm volatile("s_waitcnt lgkmcnt(" #n ")" ::: "memory")
; #define PG8_BAR __builtin_amdgcn_s_barrier()
; #define PG8_SCHED __builtin_amdgcn_sched_barrier(0)
; template <class Epi, class Sched, bool ALIGN_EPI = false, bool SP2 = false>
; __device__ __forceinline__ void gemm_phase(PG8_LAS unsigned char* lds, const Gemm g, const Sched& S, const Epi& E) {
;     ...
;             PG8_WAIT_V(8); PG8_WAIT_L(0); PG8_BAR; PG8_MMA(1, 0, At, B0); PG8_MMA(1, 1, At, B1); PG8_BAR; PG8_SCHED;
;             PG8_LDB(B0, 1, 0); PG8_LDB(B1, 1, 1); PG8_SCHED; PG8_LDA(At, 1, 0); PG8_STAGE(PG8_SA(0, 1), a2 + hstepA, voffA);
;             PG8_WAIT_V(8); PG8_WAIT_L(0); PG8_BAR; PG8_MMA(0, 0, At, B0); PG8_MMA(0, 1, At, B1); PG8_BAR; PG8_SCHED;
	s_setprio 1
	v_mfma_f32_16x16x32_bf16 v[60:63], v[144:147], v[184:187], v[60:63]
	v_mfma_f32_16x16x32_bf16 v[56:59], v[156:159], v[184:187], v[56:59]
	v_mfma_f32_16x16x32_bf16 v[44:47], v[144:147], v[192:195], v[44:47]
	v_mfma_f32_16x16x32_bf16 v[40:43], v[156:159], v[192:195], v[40:43]
	v_mfma_f32_16x16x32_bf16 v[28:31], v[144:147], v[200:203], v[28:31]
	v_mfma_f32_16x16x32_bf16 v[24:27], v[156:159], v[200:203], v[24:27]
	v_mfma_f32_16x16x32_bf16 v[12:15], v[144:147], v[208:211], v[12:15]
	v_mfma_f32_16x16x32_bf16 v[8:11], v[156:159], v[208:211], v[8:11]
	v_mfma_f32_16x16x32_bf16 v[60:63], v[152:155], v[188:191], v[60:63]
	v_mfma_f32_16x16x32_bf16 v[56:59], v[160:163], v[188:191], v[56:59]
	v_mfma_f32_16x16x32_bf16 v[44:47], v[152:155], v[196:199], v[44:47]
	v_mfma_f32_16x16x32_bf16 v[40:43], v[160:163], v[196:199], v[40:43]
	v_mfma_f32_16x16x32_bf16 v[28:31], v[152:155], v[204:207], v[28:31]
	v_mfma_f32_16x16x32_bf16 v[24:27], v[160:163], v[204:207], v[24:27]
	v_mfma_f32_16x16x32_bf16 v[12:15], v[152:155], v[212:215], v[12:15]
	v_mfma_f32_16x16x32_bf16 v[8:11], v[160:163], v[212:215], v[8:11]
	v_mfma_f32_16x16x32_bf16 v[52:55], v[168:171], v[184:187], v[52:55]
	v_mfma_f32_16x16x32_bf16 v[48:51], v[176:179], v[184:187], v[48:51]
	v_mfma_f32_16x16x32_bf16 v[36:39], v[168:171], v[192:195], v[36:39]
	v_mfma_f32_16x16x32_bf16 v[32:35], v[176:179], v[192:195], v[32:35]
	v_mfma_f32_16x16x32_bf16 v[20:23], v[168:171], v[200:203], v[20:23]
	v_mfma_f32_16x16x32_bf16 v[16:19], v[176:179], v[200:203], v[16:19]
	v_mfma_f32_16x16x32_bf16 v[4:7], v[168:171], v[208:211], v[4:7]
	v_mfma_f32_16x16x32_bf16 v[0:3], v[176:179], v[208:211], v[0:3]
	v_mfma_f32_16x16x32_bf16 v[52:55], v[172:175], v[188:191], v[52:55]
	v_mfma_f32_16x16x32_bf16 v[48:51], v[180:183], v[188:191], v[48:51]
	v_mfma_f32_16x16x32_bf16 v[36:39], v[172:175], v[196:199], v[36:39]
	v_mfma_f32_16x16x32_bf16 v[32:35], v[180:183], v[196:199], v[32:35]
	v_mfma_f32_16x16x32_bf16 v[20:23], v[172:175], v[204:207], v[20:23]
	v_mfma_f32_16x16x32_bf16 v[16:19], v[180:183], v[204:207], v[16:19]
	v_mfma_f32_16x16x32_bf16 v[4:7], v[172:175], v[212:215], v[4:7]
	v_mfma_f32_16x16x32_bf16 v[0:3], v[180:183], v[212:215], v[0:3]
	s_setprio 0
	s_barrier
	s_add_i32 s4, 0, 0x18000
	s_add_i32 s5, 0, 0x1c000
	v_add_u32_e32 v160, s4, v148
	v_add_u32_e32 v166, s5, v148
	ds_read_b128 v[144:147], v160
	ds_read_b128 v[152:155], v160 offset:1024
	ds_read_b128 v[156:159], v160 offset:2048
	ds_read_b128 v[160:163], v160 offset:3072
	ds_read_b128 v[168:171], v166
	ds_read_b128 v[172:175], v166 offset:1024
	ds_read_b128 v[176:179], v166 offset:2048
	ds_read_b128 v[180:183], v166 offset:3072
	s_add_u32 s36, s36, 0x80000
	s_addc_u32 s37, s37, 0
	s_mov_b32 m0, s38
	v_lshl_add_u64 v[222:223], s[36:37], 0, v[128:129]
	ds_read_b128 v[184:187], v151 offset:32768
	ds_read_b128 v[188:191], v151 offset:33792
	ds_read_b128 v[192:195], v151 offset:34816
	ds_read_b128 v[196:199], v151 offset:35840
	ds_read_b128 v[200:203], v151 offset:36864
	ds_read_b128 v[204:207], v151 offset:37888
	ds_read_b128 v[208:211], v151 offset:38912
	ds_read_b128 v[212:215], v151 offset:39936
	global_load_lds_dwordx4 v[222:223], off
	v_lshl_add_u64 v[222:223], s[36:37], 0, v[132:133]
	s_mov_b32 m0, s39
	s_nop 0
	global_load_lds_dwordx4 v[222:223], off
	s_waitcnt vmcnt(8)
	s_waitcnt lgkmcnt(0)
	s_barrier
	s_setprio 1
	v_mfma_f32_16x16x32_bf16 v[124:127], v[144:147], v[184:187], v[124:127]
	v_mfma_f32_16x16x32_bf16 v[120:123], v[156:159], v[184:187], v[120:123]
	v_mfma_f32_16x16x32_bf16 v[108:111], v[144:147], v[192:195], v[108:111]
	v_mfma_f32_16x16x32_bf16 v[104:107], v[156:159], v[192:195], v[104:107]
	v_mfma_f32_16x16x32_bf16 v[92:95], v[144:147], v[200:203], v[92:95]
	v_mfma_f32_16x16x32_bf16 v[88:91], v[156:159], v[200:203], v[88:91]
	v_mfma_f32_16x16x32_bf16 v[76:79], v[144:147], v[208:211], v[76:79]
	v_mfma_f32_16x16x32_bf16 v[72:75], v[156:159], v[208:211], v[72:75]
	v_mfma_f32_16x16x32_bf16 v[124:127], v[152:155], v[188:191], v[124:127]
	v_mfma_f32_16x16x32_bf16 v[120:123], v[160:163], v[188:191], v[120:123]
	v_mfma_f32_16x16x32_bf16 v[108:111], v[152:155], v[196:199], v[108:111]
	v_mfma_f32_16x16x32_bf16 v[104:107], v[160:163], v[196:199], v[104:107]
	v_mfma_f32_16x16x32_bf16 v[92:95], v[152:155], v[204:207], v[92:95]
	v_mfma_f32_16x16x32_bf16 v[88:91], v[160:163], v[204:207], v[88:91]
	v_mfma_f32_16x16x32_bf16 v[76:79], v[152:155], v[212:215], v[76:79]
	v_mfma_f32_16x16x32_bf16 v[72:75], v[160:163], v[212:215], v[72:75]
	v_mfma_f32_16x16x32_bf16 v[116:119], v[168:171], v[184:187], v[116:119]
	v_mfma_f32_16x16x32_bf16 v[112:115], v[176:179], v[184:187], v[112:115]
	v_mfma_f32_16x16x32_bf16 v[100:103], v[168:171], v[192:195], v[100:103]
	v_mfma_f32_16x16x32_bf16 v[96:99], v[176:179], v[192:195], v[96:99]
	v_mfma_f32_16x16x32_bf16 v[84:87], v[168:171], v[200:203], v[84:87]
	v_mfma_f32_16x16x32_bf16 v[80:83], v[176:179], v[200:203], v[80:83]
	v_mfma_f32_16x16x32_bf16 v[68:71], v[168:171], v[208:211], v[68:71]
	v_mfma_f32_16x16x32_bf16 v[64:67], v[176:179], v[208:211], v[64:67]
	v_mfma_f32_16x16x32_bf16 v[116:119], v[172:175], v[188:191], v[116:119]
	v_mfma_f32_16x16x32_bf16 v[112:115], v[180:183], v[188:191], v[112:115]
	v_mfma_f32_16x16x32_bf16 v[100:103], v[172:175], v[196:199], v[100:103]
	v_mfma_f32_16x16x32_bf16 v[96:99], v[180:183], v[196:199], v[96:99]
	v_mfma_f32_16x16x32_bf16 v[84:87], v[172:175], v[204:207], v[84:87]
	v_mfma_f32_16x16x32_bf16 v[80:83], v[180:183], v[204:207], v[80:83]
	v_mfma_f32_16x16x32_bf16 v[68:71], v[172:175], v[212:215], v[68:71]
	v_mfma_f32_16x16x32_bf16 v[64:67], v[180:183], v[212:215], v[64:67]
	s_setprio 0
	s_barrier
; #define PG8_STAGE(bufoff, gbase, voff) do { _Pragma("unroll") for (int _i = 0; _i < 2; ++_i) \
;         __builtin_amdgcn_global_load_lds((const unsigned*)((const char*)(gbase) + (voff)[_i]), (PG8_LAS unsigned*)(lds + (bufoff) + ldsw + _i * 8192), 16, 0, 0); } while (0)
; #define PG8_LDA(dst, b, h) do { _Pragma("unroll") for (int m = 0; m < 4; ++m) _Pragma("unroll") for (int k = 0; k < 2; ++k) dst[m][k] = *(const PG8_LAS bf16x8*)(lds + PG8_SA(b, h) + aoff + m * 2048 + k * 1024); } while (0)
; #define PG8_MMA(ai, bj, At, Bt) do { __builtin_amdgcn_s_setprio(1); _Pragma("unroll") for (int m = 0; m < 4; ++m) _Pragma("unroll") for (int n = 0; n < 2; ++n) _Pragma("unroll") for (int k = 0; k < 2; ++k) \
;         acc[ai][bj][m][n] = __builtin_amdgcn_mfma_f32_16x16x32_bf16(Bt[n][k], At[m][k], acc[ai][bj][m][n], 0, 0, 0); __builtin_amdgcn_s_setprio(0); } while (0)
; #define PG8_WAIT_V(n) asm volatile("s_waitcnt vmcnt(" #n ")" ::: "memory")
; #define PG8_WAIT_L(n) asm volatile("s_waitcnt lgkmcnt(" #n ")" ::: "memory")
; #define PG8_BAR __builtin_amdgcn_s_barrier()
; #define PG8_SCHED __builtin_amdgcn_sched_barrier(0)
; template <class Epi, class Sched, bool ALIGN_EPI = false, bool SP2 = false>
; __device__ __forceinline__ void gemm_phase(PG8_LAS unsigned char* lds, const Gemm g, const Sched& S, const Epi& E) {
;     ...
;         for (int t = 0; t < nt; t += 2) {
;     ...
;             PG8_LDA(At, 1, 1); PG8_STAGE(PG8_SB(1, 0), b3, voffB); PG8_STAGE(PG8_SB(1, 1), b3 + hstepB, voffB); PG8_STAGE(PG8_SA(1, 0), a3, voffA);
;             PG8_WAIT_V(8); PG8_WAIT_L(0); PG8_BAR; PG8_MMA(1, 0, At, B0); PG8_MMA(1, 1, At, B1); PG8_BAR; PG8_SCHED;
	s_add_i32 s4, s4, s47
	v_lshl_add_u64 v[164:165], v[164:165], 0, s[16:17]
	s_mov_b32 m0, s4
	ds_read_b128 v[184:187], v151 offset:49152
	ds_read_b128 v[188:191], v151 offset:50176
	ds_read_b128 v[192:195], v151 offset:51200
	ds_read_b128 v[196:199], v151 offset:52224
	ds_read_b128 v[200:203], v151 offset:53248
	ds_read_b128 v[204:207], v151 offset:54272
	ds_read_b128 v[208:211], v151 offset:55296
	ds_read_b128 v[212:215], v151 offset:56320
	global_load_lds_dwordx4 v[164:165], off
	s_add_i32 m0, s4, 0x2000
	s_add_u32 s34, s34, 0x80080
	v_lshl_add_u64 v[164:165], v[216:217], 0, s[16:17]
	s_addc_u32 s35, s35, 0
	s_add_i32 s4, s5, s47
	global_load_lds_dwordx4 v[164:165], off
	v_lshl_add_u64 v[164:165], s[34:35], 0, v[130:131]
	s_mov_b32 m0, s4
	s_nop 0
	global_load_lds_dwordx4 v[164:165], off
	v_lshl_add_u64 v[164:165], s[34:35], 0, v[134:135]
	s_add_i32 m0, s4, 0x2000
	s_nop 0
	global_load_lds_dwordx4 v[164:165], off
	v_lshl_add_u64 v[164:165], v[218:219], 0, s[16:17]
	s_mov_b32 m0, s40
	s_nop 0
	global_load_lds_dwordx4 v[164:165], off
	v_lshl_add_u64 v[164:165], v[220:221], 0, s[16:17]
	s_mov_b32 m0, s41
	s_nop 0
	global_load_lds_dwordx4 v[164:165], off
	s_waitcnt vmcnt(8)
	s_waitcnt lgkmcnt(0)
	s_barrier
	s_setprio 1
	v_mfma_f32_16x16x32_bf16 v[60:63], v[144:147], v[184:187], v[60:63]
	v_mfma_f32_16x16x32_bf16 v[56:59], v[156:159], v[184:187], v[56:59]
	v_mfma_f32_16x16x32_bf16 v[44:47], v[144:147], v[192:195], v[44:47]
	v_mfma_f32_16x16x32_bf16 v[40:43], v[156:159], v[192:195], v[40:43]
	v_mfma_f32_16x16x32_bf16 v[28:31], v[144:147], v[200:203], v[28:31]
	v_mfma_f32_16x16x32_bf16 v[24:27], v[156:159], v[200:203], v[24:27]
	v_mfma_f32_16x16x32_bf16 v[12:15], v[144:147], v[208:211], v[12:15]
	v_mfma_f32_16x16x32_bf16 v[8:11], v[156:159], v[208:211], v[8:11]
	v_mfma_f32_16x16x32_bf16 v[60:63], v[152:155], v[188:191], v[60:63]
	v_mfma_f32_16x16x32_bf16 v[56:59], v[160:163], v[188:191], v[56:59]
	v_mfma_f32_16x16x32_bf16 v[44:47], v[152:155], v[196:199], v[44:47]
	v_mfma_f32_16x16x32_bf16 v[40:43], v[160:163], v[196:199], v[40:43]
	v_mfma_f32_16x16x32_bf16 v[28:31], v[152:155], v[204:207], v[28:31]
	v_mfma_f32_16x16x32_bf16 v[24:27], v[160:163], v[204:207], v[24:27]
	v_mfma_f32_16x16x32_bf16 v[12:15], v[152:155], v[212:215], v[12:15]
	v_mfma_f32_16x16x32_bf16 v[8:11], v[160:163], v[212:215], v[8:11]
	v_mfma_f32_16x16x32_bf16 v[52:55], v[168:171], v[184:187], v[52:55]
	v_mfma_f32_16x16x32_bf16 v[48:51], v[176:179], v[184:187], v[48:51]
	v_mfma_f32_16x16x32_bf16 v[36:39], v[168:171], v[192:195], v[36:39]
	v_mfma_f32_16x16x32_bf16 v[32:35], v[176:179], v[192:195], v[32:35]
	v_mfma_f32_16x16x32_bf16 v[20:23], v[168:171], v[200:203], v[20:23]
	v_mfma_f32_16x16x32_bf16 v[16:19], v[176:179], v[200:203], v[16:19]
	v_mfma_f32_16x16x32_bf16 v[4:7], v[168:171], v[208:211], v[4:7]
	v_mfma_f32_16x16x32_bf16 v[0:3], v[176:179], v[208:211], v[0:3]
	v_mfma_f32_16x16x32_bf16 v[52:55], v[172:175], v[188:191], v[52:55]
	v_mfma_f32_16x16x32_bf16 v[48:51], v[180:183], v[188:191], v[48:51]
	v_mfma_f32_16x16x32_bf16 v[36:39], v[172:175], v[196:199], v[36:39]
	v_mfma_f32_16x16x32_bf16 v[32:35], v[180:183], v[196:199], v[32:35]
	v_mfma_f32_16x16x32_bf16 v[20:23], v[172:175], v[204:207], v[20:23]
	v_mfma_f32_16x16x32_bf16 v[16:19], v[180:183], v[204:207], v[16:19]
	v_mfma_f32_16x16x32_bf16 v[4:7], v[172:175], v[212:215], v[4:7]
	v_mfma_f32_16x16x32_bf16 v[0:3], v[180:183], v[212:215], v[0:3]
	s_add_i32 s56, s56, 2
	s_add_u32 s30, s30, 0x100
	s_addc_u32 s31, s31, 0
	s_add_u32 s54, s54, 0x100
	s_addc_u32 s55, s55, 0
	s_cmp_gt_u32 s56, 29
	s_setprio 0
	s_barrier
	s_cbranch_scc0 .LBB0_660
	s_and_b64 vcc, exec, s[48:49]
	s_cbranch_vccz .LBB0_663
	s_barrier

; #define PG8_STAGE(bufoff, gbase, voff) do { _Pragma("unroll") for (int _i = 0; _i < 2; ++_i) \
;         __builtin_amdgcn_global_load_lds((const unsigned*)((const char*)(gbase) + (voff)[_i]), (PG8_LAS unsigned*)(lds + (bufoff) + ldsw + _i * 8192), 16, 0, 0); } while (0)
; #define PG8_LDA(dst, b, h) do { _Pragma("unroll") for (int m = 0; m < 4; ++m) _Pragma("unroll") for (int k = 0; k < 2; ++k) dst[m][k] = *(const PG8_LAS bf16x8*)(lds + PG8_SA(b, h) + aoff + m * 2048 + k * 1024); } while (0)
; #define PG8_LDB(dst, b, h) do { _Pragma("unroll") for (int n = 0; n < 2; ++n) _Pragma("unroll") for (int k = 0; k < 2; ++k) dst[n][k] = *(const PG8_LAS bf16x8*)(lds + PG8_SB(b, h) + boff + n * 2048 + k * 1024); } while (0)
; #define PG8_MMA(ai, bj, At, Bt) do { __builtin_amdgcn_s_setprio(1); _Pragma("unroll") for (int m = 0; m < 4; ++m) _Pragma("unroll") for (int n = 0; n < 2; ++n) _Pragma("unroll") for (int k = 0; k < 2; ++k) \
;         acc[ai][bj][m][n] = __builtin_amdgcn_mfma_f32_16x16x32_bf16(Bt[n][k], At[m][k], acc[ai][bj][m][n], 0, 0, 0); __builtin_amdgcn_s_setprio(0); } while (0)
; #define PG8_WAIT_V(n) asm volatile("s_waitcnt vmcnt(" #n ")" ::: "memory")
; #define PG8_WAIT_L(n) asm volatile("s_waitcnt lgkmcnt(" #n ")" ::: "memory")
; template <class Epi, class Sched, bool ALIGN_EPI = false, bool SP2 = false>
; __device__ __forceinline__ void gemm_phase(PG8_LAS unsigned char* lds, const Gemm g, const Sched& S, const Epi& E) {
;     ...
;             const bool last = (t == nt - 2);
;             const char* a1 = cA + (size_t)(t + 1) * kstep;
;             const char* a2 = last ? nA : cA + (size_t)(t + 2) * kstep; const char* b2 = last ? nB : cB + (size_t)(t + 2) * kstep;
;             const char* a3 = a2 + kstep; const char* b3 = b2 + kstep;
;             if (last && has_next) S.a_ready(nxt);
;             if constexpr (SP2) {
;             PG8_LDB(B0, 0, 0); PG8_LDB(B1, 0, 1); PG8_SCHED; PG8_LDA(At, 0, 0); PG8_STAGE(PG8_SA(1, 1), a1 + hstepA, voffA);
;             PG8_WAIT_V(8); PG8_WAIT_L(0); PG8_BAR; PG8_MMA(0, 0, At, B0); PG8_MMA(0, 1, At, B1); PG8_BAR; PG8_SCHED;
;             PG8_LDA(At, 0, 1); PG8_STAGE(PG8_SB(0, 0), b2, voffB); PG8_STAGE(PG8_SB(0, 1), b2 + hstepB, voffB); PG8_STAGE(PG8_SA(0, 0), a2, voffA);
;             PG8_WAIT_V(8); PG8_WAIT_L(0); PG8_BAR; PG8_MMA(1, 0, At, B0); PG8_MMA(1, 1, At, B1); PG8_BAR; PG8_SCHED;
.LBB0_736:
	ds_read_b128 v[144:147], v149
	ds_read_b128 v[154:157], v149 offset:1024
	ds_read_b128 v[158:161], v149 offset:2048
	ds_read_b128 v[162:165], v149 offset:3072
	ds_read_b128 v[168:171], v150
	ds_read_b128 v[172:175], v150 offset:1024
	ds_read_b128 v[176:179], v150 offset:2048
	ds_read_b128 v[180:183], v150 offset:3072
	s_add_u32 s4, s28, 0xfff80080
	s_addc_u32 s5, s29, -1
	s_cmp_eq_u32 s60, 28
	s_cselect_b32 s35, s19, s5
	s_cselect_b32 s34, s56, s4
	s_cselect_b32 s31, s17, s59
	s_cselect_b32 s30, s57, s58
	v_lshl_add_u64 v[216:217], s[28:29], 0, v[136:137]
	s_add_i32 m0, s27, 0xc000
	ds_read_b128 v[184:187], v151
	ds_read_b128 v[188:191], v151 offset:1024
	ds_read_b128 v[192:195], v151 offset:2048
	ds_read_b128 v[196:199], v151 offset:3072
	ds_read_b128 v[200:203], v151 offset:4096
	ds_read_b128 v[204:207], v151 offset:5120
	ds_read_b128 v[208:211], v151 offset:6144
	ds_read_b128 v[212:215], v151 offset:7168
	global_load_lds_dwordx4 v[216:217], off
	v_lshl_add_u64 v[216:217], s[28:29], 0, v[138:139]
	s_add_i32 m0, s27, 0xe000
	s_nop 0
	global_load_lds_dwordx4 v[216:217], off
	s_waitcnt vmcnt(8)
	s_waitcnt lgkmcnt(0)
	s_barrier
	s_setprio 1
	v_mfma_f32_16x16x32_bf16 v[116:119], v[144:147], v[184:187], v[116:119]
	v_mfma_f32_16x16x32_bf16 v[112:115], v[158:161], v[184:187], v[112:115]
	v_mfma_f32_16x16x32_bf16 v[100:103], v[144:147], v[192:195], v[100:103]
	v_mfma_f32_16x16x32_bf16 v[96:99], v[158:161], v[192:195], v[96:99]
	v_mfma_f32_16x16x32_bf16 v[84:87], v[144:147], v[200:203], v[84:87]
	v_mfma_f32_16x16x32_bf16 v[80:83], v[158:161], v[200:203], v[80:83]
	v_mfma_f32_16x16x32_bf16 v[68:71], v[144:147], v[208:211], v[68:71]
	v_mfma_f32_16x16x32_bf16 v[64:67], v[158:161], v[208:211], v[64:67]
	v_mfma_f32_16x16x32_bf16 v[116:119], v[154:157], v[188:191], v[116:119]
	v_mfma_f32_16x16x32_bf16 v[112:115], v[162:165], v[188:191], v[112:115]
	v_mfma_f32_16x16x32_bf16 v[100:103], v[154:157], v[196:199], v[100:103]
	v_mfma_f32_16x16x32_bf16 v[96:99], v[162:165], v[196:199], v[96:99]
	v_mfma_f32_16x16x32_bf16 v[84:87], v[154:157], v[204:207], v[84:87]
	v_mfma_f32_16x16x32_bf16 v[80:83], v[162:165], v[204:207], v[80:83]
	v_mfma_f32_16x16x32_bf16 v[68:71], v[154:157], v[212:215], v[68:71]
	v_mfma_f32_16x16x32_bf16 v[64:67], v[162:165], v[212:215], v[64:67]
	v_mfma_f32_16x16x32_bf16 v[124:127], v[168:171], v[184:187], v[124:127]
	v_mfma_f32_16x16x32_bf16 v[120:123], v[176:179], v[184:187], v[120:123]
	v_mfma_f32_16x16x32_bf16 v[108:111], v[168:171], v[192:195], v[108:111]
	v_mfma_f32_16x16x32_bf16 v[104:107], v[176:179], v[192:195], v[104:107]
	v_mfma_f32_16x16x32_bf16 v[92:95], v[168:171], v[200:203], v[92:95]
	v_mfma_f32_16x16x32_bf16 v[88:91], v[176:179], v[200:203], v[88:91]
	v_mfma_f32_16x16x32_bf16 v[76:79], v[168:171], v[208:211], v[76:79]
	v_mfma_f32_16x16x32_bf16 v[72:75], v[176:179], v[208:211], v[72:75]
	v_mfma_f32_16x16x32_bf16 v[124:127], v[172:175], v[188:191], v[124:127]
	v_mfma_f32_16x16x32_bf16 v[120:123], v[180:183], v[188:191], v[120:123]
	v_mfma_f32_16x16x32_bf16 v[108:111], v[172:175], v[196:199], v[108:111]
	v_mfma_f32_16x16x32_bf16 v[104:107], v[180:183], v[196:199], v[104:107]
	v_mfma_f32_16x16x32_bf16 v[92:95], v[172:175], v[204:207], v[92:95]
	v_mfma_f32_16x16x32_bf16 v[88:91], v[180:183], v[204:207], v[88:91]
	v_mfma_f32_16x16x32_bf16 v[76:79], v[172:175], v[212:215], v[76:79]
	v_mfma_f32_16x16x32_bf16 v[72:75], v[180:183], v[212:215], v[72:75]
	s_setprio 0
	s_barrier
	s_add_i32 s4, s41, s47
	v_lshl_add_u64 v[216:217], s[30:31], 0, v[132:133]
	s_mov_b32 m0, s4
	ds_read_b128 v[184:187], v151 offset:16384
	ds_read_b128 v[188:191], v151 offset:17408
	ds_read_b128 v[192:195], v151 offset:18432
	ds_read_b128 v[196:199], v151 offset:19456
	ds_read_b128 v[200:203], v151 offset:20480
	ds_read_b128 v[204:207], v151 offset:21504
	ds_read_b128 v[208:211], v151 offset:22528
	ds_read_b128 v[212:215], v151 offset:23552
	global_load_lds_dwordx4 v[216:217], off
	s_add_i32 m0, s4, 0x2000
	s_add_u32 s4, s30, 0x80000
	v_lshl_add_u64 v[218:219], s[30:31], 0, v[128:129]
	s_addc_u32 s5, s31, 0
	s_add_i32 s61, s44, s47
	global_load_lds_dwordx4 v[218:219], off
	v_lshl_add_u64 v[220:221], s[4:5], 0, v[132:133]
	s_mov_b32 m0, s61
	v_lshl_add_u64 v[222:223], s[34:35], 0, v[130:131]
	global_load_lds_dwordx4 v[220:221], off
	v_lshl_add_u64 v[220:221], s[4:5], 0, v[128:129]
	s_add_i32 m0, s61, 0x2000
	s_nop 0
	global_load_lds_dwordx4 v[220:221], off
	v_lshl_add_u64 v[220:221], s[34:35], 0, v[134:135]
	s_mov_b32 m0, s27
	s_nop 0
	global_load_lds_dwordx4 v[220:221], off
	s_mov_b32 m0, s33
	s_nop 0
	global_load_lds_dwordx4 v[222:223], off
	s_waitcnt vmcnt(8)
	s_waitcnt lgkmcnt(0)
	s_barrier
; #define PG8_STAGE(bufoff, gbase, voff) do { _Pragma("unroll") for (int _i = 0; _i < 2; ++_i) \
;         __builtin_amdgcn_global_load_lds((const unsigned*)((const char*)(gbase) + (voff)[_i]), (PG8_LAS unsigned*)(lds + (bufoff) + ldsw + _i * 8192), 16, 0, 0); } while (0)
; #define PG8_LDA(dst, b, h) do { _Pragma("unroll") for (int m = 0; m < 4; ++m) _Pragma("unroll") for (int k = 0; k < 2; ++k) dst[m][k] = *(const PG8_LAS bf16x8*)(lds + PG8_SA(b, h) + aoff + m * 2048 + k * 1024); } while (0)
; #define PG8_LDB(dst, b, h) do { _Pragma("unroll") for (int n = 0; n < 2; ++n) _Pragma("unroll") for (int k = 0; k < 2; ++k) dst[n][k] = *(const PG8_LAS bf16x8*)(lds + PG8_SB(b, h) + boff + n * 2048 + k * 1024); } while (0)
; #define PG8_MMA(ai, bj, At, Bt) do { __builtin_amdgcn_s_setprio(1); _Pragma("unroll") for (int m = 0; m < 4; ++m) _Pragma("unroll") for (int n = 0; n < 2; ++n) _Pragma("unroll") for (int k = 0; k < 2; ++k) \
;         acc[ai][bj][m][n] = __builtin_amdgcn_mfma_f32_16x16x32_bf16(Bt[n][k], At[m][k], acc[ai][bj][m][n], 0, 0, 0); __builtin_amdgcn_s_setprio(0); } while (0)
; #define PG8_WAIT_V(n) asm volatile("s_waitcnt vmcnt(" #n ")" ::: "memory")
; #define PG8_WAIT_L(n) asm volatile("s_waitcnt lgkmcnt(" #n ")" ::: "memory")
; #define PG8_BAR __builtin_amdgcn_s_barrier()
; #define PG8_SCHED __builtin_amdgcn_sched_barrier(0)
; template <class Epi, class Sched, bool ALIGN_EPI = false, bool SP2 = false>
; __device__ __forceinline__ void gemm_phase(PG8_LAS unsigned char* lds, const Gemm g, const Sched& S, const Epi& E) {
;     ...
;             PG8_WAIT_V(8); PG8_WAIT_L(0); PG8_BAR; PG8_MMA(1, 0, At, B0); PG8_MMA(1, 1, At, B1); PG8_BAR; PG8_SCHED;
;             PG8_LDB(B0, 1, 0); PG8_LDB(B1, 1, 1); PG8_SCHED; PG8_LDA(At, 1, 0); PG8_STAGE(PG8_SA(0, 1), a2 + hstepA, voffA);
;             PG8_WAIT_V(8); PG8_WAIT_L(0); PG8_BAR; PG8_MMA(0, 0, At, B0); PG8_MMA(0, 1, At, B1); PG8_BAR; PG8_SCHED;
	s_setprio 1
	v_mfma_f32_16x16x32_bf16 v[52:55], v[144:147], v[184:187], v[52:55]
	v_mfma_f32_16x16x32_bf16 v[48:51], v[158:161], v[184:187], v[48:51]
	v_mfma_f32_16x16x32_bf16 v[36:39], v[144:147], v[192:195], v[36:39]
	v_mfma_f32_16x16x32_bf16 v[32:35], v[158:161], v[192:195], v[32:35]
	v_mfma_f32_16x16x32_bf16 v[20:23], v[144:147], v[200:203], v[20:23]
	v_mfma_f32_16x16x32_bf16 v[16:19], v[158:161], v[200:203], v[16:19]
	v_mfma_f32_16x16x32_bf16 v[8:11], v[144:147], v[208:211], v[8:11]
	v_mfma_f32_16x16x32_bf16 v[4:7], v[158:161], v[208:211], v[4:7]
	v_mfma_f32_16x16x32_bf16 v[52:55], v[154:157], v[188:191], v[52:55]
	v_mfma_f32_16x16x32_bf16 v[48:51], v[162:165], v[188:191], v[48:51]
	v_mfma_f32_16x16x32_bf16 v[36:39], v[154:157], v[196:199], v[36:39]
	v_mfma_f32_16x16x32_bf16 v[32:35], v[162:165], v[196:199], v[32:35]
	v_mfma_f32_16x16x32_bf16 v[20:23], v[154:157], v[204:207], v[20:23]
	v_mfma_f32_16x16x32_bf16 v[16:19], v[162:165], v[204:207], v[16:19]
	v_mfma_f32_16x16x32_bf16 v[8:11], v[154:157], v[212:215], v[8:11]
	v_mfma_f32_16x16x32_bf16 v[4:7], v[162:165], v[212:215], v[4:7]
	v_mfma_f32_16x16x32_bf16 v[60:63], v[168:171], v[184:187], v[60:63]
	v_mfma_f32_16x16x32_bf16 v[56:59], v[176:179], v[184:187], v[56:59]
	v_mfma_f32_16x16x32_bf16 v[44:47], v[168:171], v[192:195], v[44:47]
	v_mfma_f32_16x16x32_bf16 v[40:43], v[176:179], v[192:195], v[40:43]
	v_mfma_f32_16x16x32_bf16 v[28:31], v[168:171], v[200:203], v[28:31]
	v_mfma_f32_16x16x32_bf16 v[24:27], v[176:179], v[200:203], v[24:27]
	v_mfma_f32_16x16x32_bf16 v[12:15], v[168:171], v[208:211], v[12:15]
	v_mfma_f32_16x16x32_bf16 v[0:3], v[176:179], v[208:211], v[0:3]
	v_mfma_f32_16x16x32_bf16 v[60:63], v[172:175], v[188:191], v[60:63]
	v_mfma_f32_16x16x32_bf16 v[56:59], v[180:183], v[188:191], v[56:59]
	v_mfma_f32_16x16x32_bf16 v[44:47], v[172:175], v[196:199], v[44:47]
	v_mfma_f32_16x16x32_bf16 v[40:43], v[180:183], v[196:199], v[40:43]
	v_mfma_f32_16x16x32_bf16 v[28:31], v[172:175], v[204:207], v[28:31]
	v_mfma_f32_16x16x32_bf16 v[24:27], v[180:183], v[204:207], v[24:27]
	v_mfma_f32_16x16x32_bf16 v[12:15], v[172:175], v[212:215], v[12:15]
	v_mfma_f32_16x16x32_bf16 v[0:3], v[180:183], v[212:215], v[0:3]
	s_setprio 0
	s_barrier
	s_add_i32 s61, 0, 0x18000
	v_add_u32_e32 v153, s61, v148
	s_add_i32 s62, 0, 0x1c000
	ds_read_b128 v[144:147], v153
	ds_read_b128 v[154:157], v153 offset:1024
	ds_read_b128 v[158:161], v153 offset:2048
	ds_read_b128 v[162:165], v153 offset:3072
	v_add_u32_e32 v153, s62, v148
	ds_read_b128 v[168:171], v153
	ds_read_b128 v[172:175], v153 offset:1024
	ds_read_b128 v[176:179], v153 offset:2048
	ds_read_b128 v[180:183], v153 offset:3072
	s_add_u32 s4, s34, 0x80000
	s_addc_u32 s5, s35, 0
	s_mov_b32 m0, s36
	v_lshl_add_u64 v[224:225], s[4:5], 0, v[134:135]
	ds_read_b128 v[184:187], v151 offset:32768
	ds_read_b128 v[188:191], v151 offset:33792
	ds_read_b128 v[192:195], v151 offset:34816
	ds_read_b128 v[196:199], v151 offset:35840
	ds_read_b128 v[200:203], v151 offset:36864
	ds_read_b128 v[204:207], v151 offset:37888
	ds_read_b128 v[208:211], v151 offset:38912
	ds_read_b128 v[212:215], v151 offset:39936
	global_load_lds_dwordx4 v[224:225], off
	v_lshl_add_u64 v[224:225], s[4:5], 0, v[130:131]
	s_mov_b32 m0, s37
	s_nop 0
	global_load_lds_dwordx4 v[224:225], off
	s_waitcnt vmcnt(8)
	s_waitcnt lgkmcnt(0)
	s_barrier
	s_setprio 1
	v_mfma_f32_16x16x32_bf16 v[116:119], v[144:147], v[184:187], v[116:119]
	v_mfma_f32_16x16x32_bf16 v[112:115], v[158:161], v[184:187], v[112:115]
	v_mfma_f32_16x16x32_bf16 v[100:103], v[144:147], v[192:195], v[100:103]
	v_mfma_f32_16x16x32_bf16 v[96:99], v[158:161], v[192:195], v[96:99]
	v_mfma_f32_16x16x32_bf16 v[84:87], v[144:147], v[200:203], v[84:87]
	v_mfma_f32_16x16x32_bf16 v[80:83], v[158:161], v[200:203], v[80:83]
	v_mfma_f32_16x16x32_bf16 v[68:71], v[144:147], v[208:211], v[68:71]
	v_mfma_f32_16x16x32_bf16 v[64:67], v[158:161], v[208:211], v[64:67]
	v_mfma_f32_16x16x32_bf16 v[116:119], v[154:157], v[188:191], v[116:119]
	v_mfma_f32_16x16x32_bf16 v[112:115], v[162:165], v[188:191], v[112:115]
	v_mfma_f32_16x16x32_bf16 v[100:103], v[154:157], v[196:199], v[100:103]
	v_mfma_f32_16x16x32_bf16 v[96:99], v[162:165], v[196:199], v[96:99]
	v_mfma_f32_16x16x32_bf16 v[84:87], v[154:157], v[204:207], v[84:87]
	v_mfma_f32_16x16x32_bf16 v[80:83], v[162:165], v[204:207], v[80:83]
	v_mfma_f32_16x16x32_bf16 v[68:71], v[154:157], v[212:215], v[68:71]
	v_mfma_f32_16x16x32_bf16 v[64:67], v[162:165], v[212:215], v[64:67]
	v_mfma_f32_16x16x32_bf16 v[124:127], v[168:171], v[184:187], v[124:127]
	v_mfma_f32_16x16x32_bf16 v[120:123], v[176:179], v[184:187], v[120:123]
	v_mfma_f32_16x16x32_bf16 v[108:111], v[168:171], v[192:195], v[108:111]
	v_mfma_f32_16x16x32_bf16 v[104:107], v[176:179], v[192:195], v[104:107]
	v_mfma_f32_16x16x32_bf16 v[92:95], v[168:171], v[200:203], v[92:95]
	v_mfma_f32_16x16x32_bf16 v[88:91], v[176:179], v[200:203], v[88:91]
	v_mfma_f32_16x16x32_bf16 v[76:79], v[168:171], v[208:211], v[76:79]
	v_mfma_f32_16x16x32_bf16 v[72:75], v[176:179], v[208:211], v[72:75]
	v_mfma_f32_16x16x32_bf16 v[124:127], v[172:175], v[188:191], v[124:127]
	v_mfma_f32_16x16x32_bf16 v[120:123], v[180:183], v[188:191], v[120:123]
	v_mfma_f32_16x16x32_bf16 v[108:111], v[172:175], v[196:199], v[108:111]
	v_mfma_f32_16x16x32_bf16 v[104:107], v[180:183], v[196:199], v[104:107]
	v_mfma_f32_16x16x32_bf16 v[92:95], v[172:175], v[204:207], v[92:95]
	v_mfma_f32_16x16x32_bf16 v[88:91], v[180:183], v[204:207], v[88:91]
	v_mfma_f32_16x16x32_bf16 v[76:79], v[172:175], v[212:215], v[76:79]
	v_mfma_f32_16x16x32_bf16 v[72:75], v[180:183], v[212:215], v[72:75]
	s_setprio 0
	s_barrier
; #define PG8_STAGE(bufoff, gbase, voff) do { _Pragma("unroll") for (int _i = 0; _i < 2; ++_i) \
;         __builtin_amdgcn_global_load_lds((const unsigned*)((const char*)(gbase) + (voff)[_i]), (PG8_LAS unsigned*)(lds + (bufoff) + ldsw + _i * 8192), 16, 0, 0); } while (0)
; #define PG8_LDA(dst, b, h) do { _Pragma("unroll") for (int m = 0; m < 4; ++m) _Pragma("unroll") for (int k = 0; k < 2; ++k) dst[m][k] = *(const PG8_LAS bf16x8*)(lds + PG8_SA(b, h) + aoff + m * 2048 + k * 1024); } while (0)
; #define PG8_MMA(ai, bj, At, Bt) do { __builtin_amdgcn_s_setprio(1); _Pragma("unroll") for (int m = 0; m < 4; ++m) _Pragma("unroll") for (int n = 0; n < 2; ++n) _Pragma("unroll") for (int k = 0; k < 2; ++k) \
;         acc[ai][bj][m][n] = __builtin_amdgcn_mfma_f32_16x16x32_bf16(Bt[n][k], At[m][k], acc[ai][bj][m][n], 0, 0, 0); __builtin_amdgcn_s_setprio(0); } while (0)
; #define PG8_WAIT_V(n) asm volatile("s_waitcnt vmcnt(" #n ")" ::: "memory")
; #define PG8_WAIT_L(n) asm volatile("s_waitcnt lgkmcnt(" #n ")" ::: "memory")
; #define PG8_BAR __builtin_amdgcn_s_barrier()
; #define PG8_SCHED __builtin_amdgcn_sched_barrier(0)
; template <class Epi, class Sched, bool ALIGN_EPI = false, bool SP2 = false>
; __device__ __forceinline__ void gemm_phase(PG8_LAS unsigned char* lds, const Gemm g, const Sched& S, const Epi& E) {
;     ...
;         for (int t = 0; t < nt; t += 2) {
;     ...
;             PG8_LDA(At, 1, 1); PG8_STAGE(PG8_SB(1, 0), b3, voffB); PG8_STAGE(PG8_SB(1, 1), b3 + hstepB, voffB); PG8_STAGE(PG8_SA(1, 0), a3, voffA);
;             PG8_WAIT_V(8); PG8_WAIT_L(0); PG8_BAR; PG8_MMA(1, 0, At, B0); PG8_MMA(1, 1, At, B1); PG8_BAR; PG8_SCHED;
	s_add_i32 s4, s61, s47
	v_lshl_add_u64 v[216:217], v[216:217], 0, s[14:15]
	s_mov_b32 m0, s4
	ds_read_b128 v[184:187], v151 offset:49152
	ds_read_b128 v[188:191], v151 offset:50176
	ds_read_b128 v[192:195], v151 offset:51200
	ds_read_b128 v[196:199], v151 offset:52224
	ds_read_b128 v[200:203], v151 offset:53248
	ds_read_b128 v[204:207], v151 offset:54272
	ds_read_b128 v[208:211], v151 offset:55296
	ds_read_b128 v[212:215], v151 offset:56320
	global_load_lds_dwordx4 v[216:217], off
	s_add_i32 m0, s4, 0x2000
	s_add_u32 s4, s30, 0x80080
	v_lshl_add_u64 v[216:217], v[218:219], 0, s[14:15]
	s_addc_u32 s5, s31, 0
	s_add_i32 s30, s62, s47
	global_load_lds_dwordx4 v[216:217], off
	v_lshl_add_u64 v[216:217], s[4:5], 0, v[132:133]
	s_mov_b32 m0, s30
	s_nop 0
	global_load_lds_dwordx4 v[216:217], off
	v_lshl_add_u64 v[216:217], s[4:5], 0, v[128:129]
	s_add_i32 m0, s30, 0x2000
	s_nop 0
	global_load_lds_dwordx4 v[216:217], off
	v_lshl_add_u64 v[216:217], v[220:221], 0, s[14:15]
	s_mov_b32 m0, s39
	s_nop 0
	global_load_lds_dwordx4 v[216:217], off
	v_lshl_add_u64 v[216:217], v[222:223], 0, s[14:15]
	s_mov_b32 m0, s40
	s_nop 0
	global_load_lds_dwordx4 v[216:217], off
	s_waitcnt vmcnt(8)
	s_waitcnt lgkmcnt(0)
	s_barrier
	s_setprio 1
	v_mfma_f32_16x16x32_bf16 v[52:55], v[144:147], v[184:187], v[52:55]
	v_mfma_f32_16x16x32_bf16 v[48:51], v[158:161], v[184:187], v[48:51]
	v_mfma_f32_16x16x32_bf16 v[36:39], v[144:147], v[192:195], v[36:39]
	v_mfma_f32_16x16x32_bf16 v[32:35], v[158:161], v[192:195], v[32:35]
	v_mfma_f32_16x16x32_bf16 v[20:23], v[144:147], v[200:203], v[20:23]
	v_mfma_f32_16x16x32_bf16 v[16:19], v[158:161], v[200:203], v[16:19]
	v_mfma_f32_16x16x32_bf16 v[8:11], v[144:147], v[208:211], v[8:11]
	v_mfma_f32_16x16x32_bf16 v[4:7], v[158:161], v[208:211], v[4:7]
	v_mfma_f32_16x16x32_bf16 v[52:55], v[154:157], v[188:191], v[52:55]
	v_mfma_f32_16x16x32_bf16 v[48:51], v[162:165], v[188:191], v[48:51]
	v_mfma_f32_16x16x32_bf16 v[36:39], v[154:157], v[196:199], v[36:39]
	v_mfma_f32_16x16x32_bf16 v[32:35], v[162:165], v[196:199], v[32:35]
	v_mfma_f32_16x16x32_bf16 v[20:23], v[154:157], v[204:207], v[20:23]
	v_mfma_f32_16x16x32_bf16 v[16:19], v[162:165], v[204:207], v[16:19]
	v_mfma_f32_16x16x32_bf16 v[8:11], v[154:157], v[212:215], v[8:11]
	v_mfma_f32_16x16x32_bf16 v[4:7], v[162:165], v[212:215], v[4:7]
	v_mfma_f32_16x16x32_bf16 v[60:63], v[168:171], v[184:187], v[60:63]
	v_mfma_f32_16x16x32_bf16 v[56:59], v[176:179], v[184:187], v[56:59]
	v_mfma_f32_16x16x32_bf16 v[44:47], v[168:171], v[192:195], v[44:47]
	v_mfma_f32_16x16x32_bf16 v[40:43], v[176:179], v[192:195], v[40:43]
	v_mfma_f32_16x16x32_bf16 v[28:31], v[168:171], v[200:203], v[28:31]
	v_mfma_f32_16x16x32_bf16 v[24:27], v[176:179], v[200:203], v[24:27]
	v_mfma_f32_16x16x32_bf16 v[12:15], v[168:171], v[208:211], v[12:15]
	v_mfma_f32_16x16x32_bf16 v[0:3], v[176:179], v[208:211], v[0:3]
	v_mfma_f32_16x16x32_bf16 v[60:63], v[172:175], v[188:191], v[60:63]
	v_mfma_f32_16x16x32_bf16 v[56:59], v[180:183], v[188:191], v[56:59]
	v_mfma_f32_16x16x32_bf16 v[44:47], v[172:175], v[196:199], v[44:47]
	v_mfma_f32_16x16x32_bf16 v[40:43], v[180:183], v[196:199], v[40:43]
	v_mfma_f32_16x16x32_bf16 v[28:31], v[172:175], v[204:207], v[28:31]
	v_mfma_f32_16x16x32_bf16 v[24:27], v[180:183], v[204:207], v[24:27]
	v_mfma_f32_16x16x32_bf16 v[12:15], v[172:175], v[212:215], v[12:15]
	v_mfma_f32_16x16x32_bf16 v[0:3], v[180:183], v[212:215], v[0:3]
	s_add_i32 s60, s60, 2
	s_add_u32 s28, s28, 0x100
	s_addc_u32 s29, s29, 0
	s_add_u32 s58, s58, 0x100
	s_addc_u32 s59, s59, 0
	s_cmp_gt_u32 s60, 29
	s_setprio 0
	s_barrier
	s_cbranch_scc0 .LBB0_736
	s_and_b64 vcc, exec, s[48:49]
	s_cbranch_vccz .LBB0_739
	s_barrier

; #define PG8_STAGE(bufoff, gbase, voff) do { _Pragma("unroll") for (int _i = 0; _i < 2; ++_i) \
;         __builtin_amdgcn_global_load_lds((const unsigned*)((const char*)(gbase) + (voff)[_i]), (PG8_LAS unsigned*)(lds + (bufoff) + ldsw + _i * 8192), 16, 0, 0); } while (0)
; #define PG8_LDA(dst, b, h) do { _Pragma("unroll") for (int m = 0; m < 4; ++m) _Pragma("unroll") for (int k = 0; k < 2; ++k) dst[m][k] = *(const PG8_LAS bf16x8*)(lds + PG8_SA(b, h) + aoff + m * 2048 + k * 1024); } while (0)
; #define PG8_LDB(dst, b, h) do { _Pragma("unroll") for (int n = 0; n < 2; ++n) _Pragma("unroll") for (int k = 0; k < 2; ++k) dst[n][k] = *(const PG8_LAS bf16x8*)(lds + PG8_SB(b, h) + boff + n * 2048 + k * 1024); } while (0)
; #define PG8_MMA(ai, bj, At, Bt) do { __builtin_amdgcn_s_setprio(1); _Pragma("unroll") for (int m = 0; m < 4; ++m) _Pragma("unroll") for (int n = 0; n < 2; ++n) _Pragma("unroll") for (int k = 0; k < 2; ++k) \
;         acc[ai][bj][m][n] = __builtin_amdgcn_mfma_f32_16x16x32_bf16(Bt[n][k], At[m][k], acc[ai][bj][m][n], 0, 0, 0); __builtin_amdgcn_s_setprio(0); } while (0)
; #define PG8_WAIT_V(n) asm volatile("s_waitcnt vmcnt(" #n ")" ::: "memory")
; #define PG8_WAIT_L(n) asm volatile("s_waitcnt lgkmcnt(" #n ")" ::: "memory")
; template <class Epi, class Sched, bool ALIGN_EPI = false, bool SP2 = false>
; __device__ __forceinline__ void gemm_phase(PG8_LAS unsigned char* lds, const Gemm g, const Sched& S, const Epi& E) {
;     ...
;             const bool last = (t == nt - 2);
;             const char* a1 = cA + (size_t)(t + 1) * kstep;
;             const char* a2 = last ? nA : cA + (size_t)(t + 2) * kstep; const char* b2 = last ? nB : cB + (size_t)(t + 2) * kstep;
;             const char* a3 = a2 + kstep; const char* b3 = b2 + kstep;
;             if (last && has_next) S.a_ready(nxt);
;             if constexpr (SP2) {
;             PG8_LDB(B0, 0, 0); PG8_LDB(B1, 0, 1); PG8_SCHED; PG8_LDA(At, 0, 0); PG8_STAGE(PG8_SA(1, 1), a1 + hstepA, voffA);
;             PG8_WAIT_V(8); PG8_WAIT_L(0); PG8_BAR; PG8_MMA(0, 0, At, B0); PG8_MMA(0, 1, At, B1); PG8_BAR; PG8_SCHED;
;             PG8_LDA(At, 0, 1); PG8_STAGE(PG8_SB(0, 0), b2, voffB); PG8_STAGE(PG8_SB(0, 1), b2 + hstepB, voffB); PG8_STAGE(PG8_SA(0, 0), a2, voffA);
;             PG8_WAIT_V(8); PG8_WAIT_L(0); PG8_BAR; PG8_MMA(1, 0, At, B0); PG8_MMA(1, 1, At, B1); PG8_BAR; PG8_SCHED;
.LBB0_892:
	ds_read_b128 v[144:147], v155
	ds_read_b128 v[148:151], v155 offset:1024
	ds_read_b128 v[160:163], v155 offset:2048
	ds_read_b128 v[168:171], v155 offset:3072
	ds_read_b128 v[172:175], v156
	ds_read_b128 v[176:179], v156 offset:1024
	ds_read_b128 v[180:183], v156 offset:2048
	ds_read_b128 v[184:187], v156 offset:3072
	s_add_u32 s4, s30, 0xfff80080
	s_addc_u32 s5, s31, -1
	s_cmp_eq_u32 s61, 28
	s_cselect_b32 s37, s11, s5
	s_cselect_b32 s36, s13, s4
	s_cselect_b32 s35, s21, s60
	s_cselect_b32 s34, s23, s59
	v_lshl_add_u64 v[152:153], s[30:31], 0, v[136:137]
	s_add_i32 m0, s25, 0xc000
	ds_read_b128 v[188:191], v157
	ds_read_b128 v[192:195], v157 offset:1024
	ds_read_b128 v[196:199], v157 offset:2048
	ds_read_b128 v[200:203], v157 offset:3072
	ds_read_b128 v[204:207], v157 offset:4096
	ds_read_b128 v[208:211], v157 offset:5120
	ds_read_b128 v[212:215], v157 offset:6144
	ds_read_b128 v[216:219], v157 offset:7168
	global_load_lds_dwordx4 v[152:153], off
	v_lshl_add_u64 v[152:153], s[30:31], 0, v[138:139]
	s_add_i32 m0, s25, 0xe000
	s_nop 0
	global_load_lds_dwordx4 v[152:153], off
	s_waitcnt vmcnt(8)
	s_waitcnt lgkmcnt(0)
	s_barrier
	s_setprio 1
	v_mfma_f32_16x16x32_bf16 v[124:127], v[144:147], v[188:191], v[124:127]
	v_mfma_f32_16x16x32_bf16 v[120:123], v[160:163], v[188:191], v[120:123]
	v_mfma_f32_16x16x32_bf16 v[108:111], v[144:147], v[196:199], v[108:111]
	v_mfma_f32_16x16x32_bf16 v[104:107], v[160:163], v[196:199], v[104:107]
	v_mfma_f32_16x16x32_bf16 v[92:95], v[144:147], v[204:207], v[92:95]
	v_mfma_f32_16x16x32_bf16 v[88:91], v[160:163], v[204:207], v[88:91]
	v_mfma_f32_16x16x32_bf16 v[76:79], v[144:147], v[212:215], v[76:79]
	v_mfma_f32_16x16x32_bf16 v[72:75], v[160:163], v[212:215], v[72:75]
	v_mfma_f32_16x16x32_bf16 v[124:127], v[148:151], v[192:195], v[124:127]
	v_mfma_f32_16x16x32_bf16 v[120:123], v[168:171], v[192:195], v[120:123]
	v_mfma_f32_16x16x32_bf16 v[108:111], v[148:151], v[200:203], v[108:111]
	v_mfma_f32_16x16x32_bf16 v[104:107], v[168:171], v[200:203], v[104:107]
	v_mfma_f32_16x16x32_bf16 v[92:95], v[148:151], v[208:211], v[92:95]
	v_mfma_f32_16x16x32_bf16 v[88:91], v[168:171], v[208:211], v[88:91]
	v_mfma_f32_16x16x32_bf16 v[76:79], v[148:151], v[216:219], v[76:79]
	v_mfma_f32_16x16x32_bf16 v[72:75], v[168:171], v[216:219], v[72:75]
	v_mfma_f32_16x16x32_bf16 v[116:119], v[172:175], v[188:191], v[116:119]
	v_mfma_f32_16x16x32_bf16 v[112:115], v[180:183], v[188:191], v[112:115]
	v_mfma_f32_16x16x32_bf16 v[100:103], v[172:175], v[196:199], v[100:103]
	v_mfma_f32_16x16x32_bf16 v[96:99], v[180:183], v[196:199], v[96:99]
	v_mfma_f32_16x16x32_bf16 v[84:87], v[172:175], v[204:207], v[84:87]
	v_mfma_f32_16x16x32_bf16 v[80:83], v[180:183], v[204:207], v[80:83]
	v_mfma_f32_16x16x32_bf16 v[68:71], v[172:175], v[212:215], v[68:71]
	v_mfma_f32_16x16x32_bf16 v[64:67], v[180:183], v[212:215], v[64:67]
	v_mfma_f32_16x16x32_bf16 v[116:119], v[176:179], v[192:195], v[116:119]
	v_mfma_f32_16x16x32_bf16 v[112:115], v[184:187], v[192:195], v[112:115]
	v_mfma_f32_16x16x32_bf16 v[100:103], v[176:179], v[200:203], v[100:103]
	v_mfma_f32_16x16x32_bf16 v[96:99], v[184:187], v[200:203], v[96:99]
	v_mfma_f32_16x16x32_bf16 v[84:87], v[176:179], v[208:211], v[84:87]
	v_mfma_f32_16x16x32_bf16 v[80:83], v[184:187], v[208:211], v[80:83]
	v_mfma_f32_16x16x32_bf16 v[68:71], v[176:179], v[216:219], v[68:71]
	v_mfma_f32_16x16x32_bf16 v[64:67], v[184:187], v[216:219], v[64:67]
	s_setprio 0
	s_barrier
	s_add_i32 s4, s45, s47
	v_lshl_add_u64 v[152:153], s[34:35], 0, v[130:131]
	s_mov_b32 m0, s4
	ds_read_b128 v[188:191], v157 offset:16384
	ds_read_b128 v[192:195], v157 offset:17408
	ds_read_b128 v[196:199], v157 offset:18432
	ds_read_b128 v[200:203], v157 offset:19456
	ds_read_b128 v[204:207], v157 offset:20480
	ds_read_b128 v[208:211], v157 offset:21504
	ds_read_b128 v[212:215], v157 offset:22528
	ds_read_b128 v[216:219], v157 offset:23552
	global_load_lds_dwordx4 v[152:153], off
	s_add_i32 m0, s4, 0x2000
	s_add_u32 s4, s34, 0x80000
	v_lshl_add_u64 v[164:165], s[34:35], 0, v[134:135]
	s_addc_u32 s5, s35, 0
	s_add_i32 s62, s46, s47
	global_load_lds_dwordx4 v[164:165], off
	v_lshl_add_u64 v[220:221], s[4:5], 0, v[130:131]
	s_mov_b32 m0, s62
	v_lshl_add_u64 v[222:223], s[36:37], 0, v[132:133]
	global_load_lds_dwordx4 v[220:221], off
	v_lshl_add_u64 v[220:221], s[4:5], 0, v[134:135]
	s_add_i32 m0, s62, 0x2000
	s_nop 0
	global_load_lds_dwordx4 v[220:221], off
	v_lshl_add_u64 v[220:221], s[36:37], 0, v[128:129]
	s_mov_b32 m0, s25
	s_nop 0
	global_load_lds_dwordx4 v[220:221], off
	s_mov_b32 m0, s33
	s_nop 0
	global_load_lds_dwordx4 v[222:223], off
	s_waitcnt vmcnt(8)
	s_waitcnt lgkmcnt(0)
	s_barrier
; #define PG8_STAGE(bufoff, gbase, voff) do { _Pragma("unroll") for (int _i = 0; _i < 2; ++_i) \
;         __builtin_amdgcn_global_load_lds((const unsigned*)((const char*)(gbase) + (voff)[_i]), (PG8_LAS unsigned*)(lds + (bufoff) + ldsw + _i * 8192), 16, 0, 0); } while (0)
; #define PG8_LDA(dst, b, h) do { _Pragma("unroll") for (int m = 0; m < 4; ++m) _Pragma("unroll") for (int k = 0; k < 2; ++k) dst[m][k] = *(const PG8_LAS bf16x8*)(lds + PG8_SA(b, h) + aoff + m * 2048 + k * 1024); } while (0)
; #define PG8_LDB(dst, b, h) do { _Pragma("unroll") for (int n = 0; n < 2; ++n) _Pragma("unroll") for (int k = 0; k < 2; ++k) dst[n][k] = *(const PG8_LAS bf16x8*)(lds + PG8_SB(b, h) + boff + n * 2048 + k * 1024); } while (0)
; #define PG8_MMA(ai, bj, At, Bt) do { __builtin_amdgcn_s_setprio(1); _Pragma("unroll") for (int m = 0; m < 4; ++m) _Pragma("unroll") for (int n = 0; n < 2; ++n) _Pragma("unroll") for (int k = 0; k < 2; ++k) \
;         acc[ai][bj][m][n] = __builtin_amdgcn_mfma_f32_16x16x32_bf16(Bt[n][k], At[m][k], acc[ai][bj][m][n], 0, 0, 0); __builtin_amdgcn_s_setprio(0); } while (0)
; #define PG8_WAIT_V(n) asm volatile("s_waitcnt vmcnt(" #n ")" ::: "memory")
; #define PG8_WAIT_L(n) asm volatile("s_waitcnt lgkmcnt(" #n ")" ::: "memory")
; #define PG8_BAR __builtin_amdgcn_s_barrier()
; #define PG8_SCHED __builtin_amdgcn_sched_barrier(0)
; template <class Epi, class Sched, bool ALIGN_EPI = false, bool SP2 = false>
; __device__ __forceinline__ void gemm_phase(PG8_LAS unsigned char* lds, const Gemm g, const Sched& S, const Epi& E) {
;     ...
;             PG8_WAIT_V(8); PG8_WAIT_L(0); PG8_BAR; PG8_MMA(1, 0, At, B0); PG8_MMA(1, 1, At, B1); PG8_BAR; PG8_SCHED;
;             PG8_LDB(B0, 1, 0); PG8_LDB(B1, 1, 1); PG8_SCHED; PG8_LDA(At, 1, 0); PG8_STAGE(PG8_SA(0, 1), a2 + hstepA, voffA);
;             PG8_WAIT_V(8); PG8_WAIT_L(0); PG8_BAR; PG8_MMA(0, 0, At, B0); PG8_MMA(0, 1, At, B1); PG8_BAR; PG8_SCHED;
	s_setprio 1
	v_mfma_f32_16x16x32_bf16 v[60:63], v[144:147], v[188:191], v[60:63]
	v_mfma_f32_16x16x32_bf16 v[56:59], v[160:163], v[188:191], v[56:59]
	v_mfma_f32_16x16x32_bf16 v[44:47], v[144:147], v[196:199], v[44:47]
	v_mfma_f32_16x16x32_bf16 v[40:43], v[160:163], v[196:199], v[40:43]
	v_mfma_f32_16x16x32_bf16 v[28:31], v[144:147], v[204:207], v[28:31]
	v_mfma_f32_16x16x32_bf16 v[24:27], v[160:163], v[204:207], v[24:27]
	v_mfma_f32_16x16x32_bf16 v[12:15], v[144:147], v[212:215], v[12:15]
	v_mfma_f32_16x16x32_bf16 v[8:11], v[160:163], v[212:215], v[8:11]
	v_mfma_f32_16x16x32_bf16 v[60:63], v[148:151], v[192:195], v[60:63]
	v_mfma_f32_16x16x32_bf16 v[56:59], v[168:171], v[192:195], v[56:59]
	v_mfma_f32_16x16x32_bf16 v[44:47], v[148:151], v[200:203], v[44:47]
	v_mfma_f32_16x16x32_bf16 v[40:43], v[168:171], v[200:203], v[40:43]
	v_mfma_f32_16x16x32_bf16 v[28:31], v[148:151], v[208:211], v[28:31]
	v_mfma_f32_16x16x32_bf16 v[24:27], v[168:171], v[208:211], v[24:27]
	v_mfma_f32_16x16x32_bf16 v[12:15], v[148:151], v[216:219], v[12:15]
	v_mfma_f32_16x16x32_bf16 v[8:11], v[168:171], v[216:219], v[8:11]
	v_mfma_f32_16x16x32_bf16 v[52:55], v[172:175], v[188:191], v[52:55]
	v_mfma_f32_16x16x32_bf16 v[48:51], v[180:183], v[188:191], v[48:51]
	v_mfma_f32_16x16x32_bf16 v[36:39], v[172:175], v[196:199], v[36:39]
	v_mfma_f32_16x16x32_bf16 v[32:35], v[180:183], v[196:199], v[32:35]
	v_mfma_f32_16x16x32_bf16 v[20:23], v[172:175], v[204:207], v[20:23]
	v_mfma_f32_16x16x32_bf16 v[16:19], v[180:183], v[204:207], v[16:19]
	v_mfma_f32_16x16x32_bf16 v[4:7], v[172:175], v[212:215], v[4:7]
	v_mfma_f32_16x16x32_bf16 v[0:3], v[180:183], v[212:215], v[0:3]
	v_mfma_f32_16x16x32_bf16 v[52:55], v[176:179], v[192:195], v[52:55]
	v_mfma_f32_16x16x32_bf16 v[48:51], v[184:187], v[192:195], v[48:51]
	v_mfma_f32_16x16x32_bf16 v[36:39], v[176:179], v[200:203], v[36:39]
	v_mfma_f32_16x16x32_bf16 v[32:35], v[184:187], v[200:203], v[32:35]
	v_mfma_f32_16x16x32_bf16 v[20:23], v[176:179], v[208:211], v[20:23]
	v_mfma_f32_16x16x32_bf16 v[16:19], v[184:187], v[208:211], v[16:19]
	v_mfma_f32_16x16x32_bf16 v[4:7], v[176:179], v[216:219], v[4:7]
	v_mfma_f32_16x16x32_bf16 v[0:3], v[184:187], v[216:219], v[0:3]
	s_setprio 0
	s_barrier
	s_add_i32 s62, 0, 0x18000
	v_add_u32_e32 v166, s62, v154
	s_add_i32 s63, 0, 0x1c000
	ds_read_b128 v[144:147], v166
	ds_read_b128 v[148:151], v166 offset:1024
	ds_read_b128 v[160:163], v166 offset:2048
	ds_read_b128 v[168:171], v166 offset:3072
	v_add_u32_e32 v166, s63, v154
	ds_read_b128 v[172:175], v166
	ds_read_b128 v[176:179], v166 offset:1024
	ds_read_b128 v[180:183], v166 offset:2048
	ds_read_b128 v[184:187], v166 offset:3072
	s_add_u32 s4, s36, 0x80000
	s_addc_u32 s5, s37, 0
	s_mov_b32 m0, s38
	v_lshl_add_u64 v[224:225], s[4:5], 0, v[128:129]
	ds_read_b128 v[188:191], v157 offset:32768
	ds_read_b128 v[192:195], v157 offset:33792
	ds_read_b128 v[196:199], v157 offset:34816
	ds_read_b128 v[200:203], v157 offset:35840
	ds_read_b128 v[204:207], v157 offset:36864
	ds_read_b128 v[208:211], v157 offset:37888
	ds_read_b128 v[212:215], v157 offset:38912
	ds_read_b128 v[216:219], v157 offset:39936
	global_load_lds_dwordx4 v[224:225], off
	v_lshl_add_u64 v[224:225], s[4:5], 0, v[132:133]
	s_mov_b32 m0, s39
	s_nop 0
	global_load_lds_dwordx4 v[224:225], off
	s_waitcnt vmcnt(8)
	s_waitcnt lgkmcnt(0)
	s_barrier
	s_setprio 1
	v_mfma_f32_16x16x32_bf16 v[124:127], v[144:147], v[188:191], v[124:127]
	v_mfma_f32_16x16x32_bf16 v[120:123], v[160:163], v[188:191], v[120:123]
	v_mfma_f32_16x16x32_bf16 v[108:111], v[144:147], v[196:199], v[108:111]
	v_mfma_f32_16x16x32_bf16 v[104:107], v[160:163], v[196:199], v[104:107]
	v_mfma_f32_16x16x32_bf16 v[92:95], v[144:147], v[204:207], v[92:95]
	v_mfma_f32_16x16x32_bf16 v[88:91], v[160:163], v[204:207], v[88:91]
	v_mfma_f32_16x16x32_bf16 v[76:79], v[144:147], v[212:215], v[76:79]
	v_mfma_f32_16x16x32_bf16 v[72:75], v[160:163], v[212:215], v[72:75]
	v_mfma_f32_16x16x32_bf16 v[124:127], v[148:151], v[192:195], v[124:127]
	v_mfma_f32_16x16x32_bf16 v[120:123], v[168:171], v[192:195], v[120:123]
	v_mfma_f32_16x16x32_bf16 v[108:111], v[148:151], v[200:203], v[108:111]
	v_mfma_f32_16x16x32_bf16 v[104:107], v[168:171], v[200:203], v[104:107]
	v_mfma_f32_16x16x32_bf16 v[92:95], v[148:151], v[208:211], v[92:95]
	v_mfma_f32_16x16x32_bf16 v[88:91], v[168:171], v[208:211], v[88:91]
	v_mfma_f32_16x16x32_bf16 v[76:79], v[148:151], v[216:219], v[76:79]
	v_mfma_f32_16x16x32_bf16 v[72:75], v[168:171], v[216:219], v[72:75]
	v_mfma_f32_16x16x32_bf16 v[116:119], v[172:175], v[188:191], v[116:119]
	v_mfma_f32_16x16x32_bf16 v[112:115], v[180:183], v[188:191], v[112:115]
	v_mfma_f32_16x16x32_bf16 v[100:103], v[172:175], v[196:199], v[100:103]
	v_mfma_f32_16x16x32_bf16 v[96:99], v[180:183], v[196:199], v[96:99]
	v_mfma_f32_16x16x32_bf16 v[84:87], v[172:175], v[204:207], v[84:87]
	v_mfma_f32_16x16x32_bf16 v[80:83], v[180:183], v[204:207], v[80:83]
	v_mfma_f32_16x16x32_bf16 v[68:71], v[172:175], v[212:215], v[68:71]
	v_mfma_f32_16x16x32_bf16 v[64:67], v[180:183], v[212:215], v[64:67]
	v_mfma_f32_16x16x32_bf16 v[116:119], v[176:179], v[192:195], v[116:119]
	v_mfma_f32_16x16x32_bf16 v[112:115], v[184:187], v[192:195], v[112:115]
	v_mfma_f32_16x16x32_bf16 v[100:103], v[176:179], v[200:203], v[100:103]
	v_mfma_f32_16x16x32_bf16 v[96:99], v[184:187], v[200:203], v[96:99]
	v_mfma_f32_16x16x32_bf16 v[84:87], v[176:179], v[208:211], v[84:87]
	v_mfma_f32_16x16x32_bf16 v[80:83], v[184:187], v[208:211], v[80:83]
	v_mfma_f32_16x16x32_bf16 v[68:71], v[176:179], v[216:219], v[68:71]
	v_mfma_f32_16x16x32_bf16 v[64:67], v[184:187], v[216:219], v[64:67]
	s_setprio 0
	s_barrier
; #define PG8_STAGE(bufoff, gbase, voff) do { _Pragma("unroll") for (int _i = 0; _i < 2; ++_i) \
;         __builtin_amdgcn_global_load_lds((const unsigned*)((const char*)(gbase) + (voff)[_i]), (PG8_LAS unsigned*)(lds + (bufoff) + ldsw + _i * 8192), 16, 0, 0); } while (0)
; #define PG8_LDA(dst, b, h) do { _Pragma("unroll") for (int m = 0; m < 4; ++m) _Pragma("unroll") for (int k = 0; k < 2; ++k) dst[m][k] = *(const PG8_LAS bf16x8*)(lds + PG8_SA(b, h) + aoff + m * 2048 + k * 1024); } while (0)
; #define PG8_MMA(ai, bj, At, Bt) do { __builtin_amdgcn_s_setprio(1); _Pragma("unroll") for (int m = 0; m < 4; ++m) _Pragma("unroll") for (int n = 0; n < 2; ++n) _Pragma("unroll") for (int k = 0; k < 2; ++k) \
;         acc[ai][bj][m][n] = __builtin_amdgcn_mfma_f32_16x16x32_bf16(Bt[n][k], At[m][k], acc[ai][bj][m][n], 0, 0, 0); __builtin_amdgcn_s_setprio(0); } while (0)
; #define PG8_WAIT_V(n) asm volatile("s_waitcnt vmcnt(" #n ")" ::: "memory")
; #define PG8_WAIT_L(n) asm volatile("s_waitcnt lgkmcnt(" #n ")" ::: "memory")
; #define PG8_BAR __builtin_amdgcn_s_barrier()
; #define PG8_SCHED __builtin_amdgcn_sched_barrier(0)
; template <class Epi, class Sched, bool ALIGN_EPI = false, bool SP2 = false>
; __device__ __forceinline__ void gemm_phase(PG8_LAS unsigned char* lds, const Gemm g, const Sched& S, const Epi& E) {
;     ...
;         for (int t = 0; t < nt; t += 2) {
;     ...
;             PG8_LDA(At, 1, 1); PG8_STAGE(PG8_SB(1, 0), b3, voffB); PG8_STAGE(PG8_SB(1, 1), b3 + hstepB, voffB); PG8_STAGE(PG8_SA(1, 0), a3, voffA);
;             PG8_WAIT_V(8); PG8_WAIT_L(0); PG8_BAR; PG8_MMA(1, 0, At, B0); PG8_MMA(1, 1, At, B1); PG8_BAR; PG8_SCHED;
	s_add_i32 s4, s62, s47
	v_lshl_add_u64 v[152:153], v[152:153], 0, s[18:19]
	s_mov_b32 m0, s4
	ds_read_b128 v[188:191], v157 offset:49152
	ds_read_b128 v[192:195], v157 offset:50176
	ds_read_b128 v[196:199], v157 offset:51200
	ds_read_b128 v[200:203], v157 offset:52224
	ds_read_b128 v[204:207], v157 offset:53248
	ds_read_b128 v[208:211], v157 offset:54272
	ds_read_b128 v[212:215], v157 offset:55296
	ds_read_b128 v[216:219], v157 offset:56320
	global_load_lds_dwordx4 v[152:153], off
	s_add_i32 m0, s4, 0x2000
	s_add_u32 s4, s34, 0x80080
	v_lshl_add_u64 v[152:153], v[164:165], 0, s[18:19]
	s_addc_u32 s5, s35, 0
	s_add_i32 s34, s63, s47
	global_load_lds_dwordx4 v[152:153], off
	v_lshl_add_u64 v[152:153], s[4:5], 0, v[130:131]
	s_mov_b32 m0, s34
	s_nop 0
	global_load_lds_dwordx4 v[152:153], off
	v_lshl_add_u64 v[152:153], s[4:5], 0, v[134:135]
	s_add_i32 m0, s34, 0x2000
	s_nop 0
	global_load_lds_dwordx4 v[152:153], off
	v_lshl_add_u64 v[152:153], v[220:221], 0, s[18:19]
	s_mov_b32 m0, s41
	s_nop 0
	global_load_lds_dwordx4 v[152:153], off
	v_lshl_add_u64 v[152:153], v[222:223], 0, s[18:19]
	s_mov_b32 m0, s44
	s_nop 0
	global_load_lds_dwordx4 v[152:153], off
	s_waitcnt vmcnt(8)
	s_waitcnt lgkmcnt(0)
	s_barrier
	s_setprio 1
	v_mfma_f32_16x16x32_bf16 v[60:63], v[144:147], v[188:191], v[60:63]
	v_mfma_f32_16x16x32_bf16 v[56:59], v[160:163], v[188:191], v[56:59]
	v_mfma_f32_16x16x32_bf16 v[44:47], v[144:147], v[196:199], v[44:47]
	v_mfma_f32_16x16x32_bf16 v[40:43], v[160:163], v[196:199], v[40:43]
	v_mfma_f32_16x16x32_bf16 v[28:31], v[144:147], v[204:207], v[28:31]
	v_mfma_f32_16x16x32_bf16 v[24:27], v[160:163], v[204:207], v[24:27]
	v_mfma_f32_16x16x32_bf16 v[12:15], v[144:147], v[212:215], v[12:15]
	v_mfma_f32_16x16x32_bf16 v[8:11], v[160:163], v[212:215], v[8:11]
	v_mfma_f32_16x16x32_bf16 v[60:63], v[148:151], v[192:195], v[60:63]
	v_mfma_f32_16x16x32_bf16 v[56:59], v[168:171], v[192:195], v[56:59]
	v_mfma_f32_16x16x32_bf16 v[44:47], v[148:151], v[200:203], v[44:47]
	v_mfma_f32_16x16x32_bf16 v[40:43], v[168:171], v[200:203], v[40:43]
	v_mfma_f32_16x16x32_bf16 v[28:31], v[148:151], v[208:211], v[28:31]
	v_mfma_f32_16x16x32_bf16 v[24:27], v[168:171], v[208:211], v[24:27]
	v_mfma_f32_16x16x32_bf16 v[12:15], v[148:151], v[216:219], v[12:15]
	v_mfma_f32_16x16x32_bf16 v[8:11], v[168:171], v[216:219], v[8:11]
	v_mfma_f32_16x16x32_bf16 v[52:55], v[172:175], v[188:191], v[52:55]
	v_mfma_f32_16x16x32_bf16 v[48:51], v[180:183], v[188:191], v[48:51]
	v_mfma_f32_16x16x32_bf16 v[36:39], v[172:175], v[196:199], v[36:39]
	v_mfma_f32_16x16x32_bf16 v[32:35], v[180:183], v[196:199], v[32:35]
	v_mfma_f32_16x16x32_bf16 v[20:23], v[172:175], v[204:207], v[20:23]
	v_mfma_f32_16x16x32_bf16 v[16:19], v[180:183], v[204:207], v[16:19]
	v_mfma_f32_16x16x32_bf16 v[4:7], v[172:175], v[212:215], v[4:7]
	v_mfma_f32_16x16x32_bf16 v[0:3], v[180:183], v[212:215], v[0:3]
	v_mfma_f32_16x16x32_bf16 v[52:55], v[176:179], v[192:195], v[52:55]
	v_mfma_f32_16x16x32_bf16 v[48:51], v[184:187], v[192:195], v[48:51]
	v_mfma_f32_16x16x32_bf16 v[36:39], v[176:179], v[200:203], v[36:39]
	v_mfma_f32_16x16x32_bf16 v[32:35], v[184:187], v[200:203], v[32:35]
	v_mfma_f32_16x16x32_bf16 v[20:23], v[176:179], v[208:211], v[20:23]
	v_mfma_f32_16x16x32_bf16 v[16:19], v[184:187], v[208:211], v[16:19]
	v_mfma_f32_16x16x32_bf16 v[4:7], v[176:179], v[216:219], v[4:7]
	v_mfma_f32_16x16x32_bf16 v[0:3], v[184:187], v[216:219], v[0:3]
	s_add_i32 s61, s61, 2
	s_add_u32 s30, s30, 0x100
	s_addc_u32 s31, s31, 0
	s_add_u32 s59, s59, 0x100
	s_addc_u32 s60, s60, 0
	s_cmp_gt_u32 s61, 29
	s_setprio 0
	s_barrier
	s_cbranch_scc0 .LBB0_892
	s_and_b64 vcc, exec, s[48:49]
	s_cbranch_vccz .LBB0_895
	s_barrier

; #define PG8_STAGE(bufoff, gbase, voff) do { _Pragma("unroll") for (int _i = 0; _i < 2; ++_i) \
;         __builtin_amdgcn_global_load_lds((const unsigned*)((const char*)(gbase) + (voff)[_i]), (PG8_LAS unsigned*)(lds + (bufoff) + ldsw + _i * 8192), 16, 0, 0); } while (0)
; #define PG8_LDA(dst, b, h) do { _Pragma("unroll") for (int m = 0; m < 4; ++m) _Pragma("unroll") for (int k = 0; k < 2; ++k) dst[m][k] = *(const PG8_LAS bf16x8*)(lds + PG8_SA(b, h) + aoff + m * 2048 + k * 1024); } while (0)
; #define PG8_LDB(dst, b, h) do { _Pragma("unroll") for (int n = 0; n < 2; ++n) _Pragma("unroll") for (int k = 0; k < 2; ++k) dst[n][k] = *(const PG8_LAS bf16x8*)(lds + PG8_SB(b, h) + boff + n * 2048 + k * 1024); } while (0)
; #define PG8_MMA(ai, bj, At, Bt) do { __builtin_amdgcn_s_setprio(1); _Pragma("unroll") for (int m = 0; m < 4; ++m) _Pragma("unroll") for (int n = 0; n < 2; ++n) _Pragma("unroll") for (int k = 0; k < 2; ++k) \
;         acc[ai][bj][m][n] = __builtin_amdgcn_mfma_f32_16x16x32_bf16(Bt[n][k], At[m][k], acc[ai][bj][m][n], 0, 0, 0); __builtin_amdgcn_s_setprio(0); } while (0)
; #define PG8_WAIT_V(n) asm volatile("s_waitcnt vmcnt(" #n ")" ::: "memory")
; #define PG8_WAIT_L(n) asm volatile("s_waitcnt lgkmcnt(" #n ")" ::: "memory")
; template <class Epi, class Sched, bool ALIGN_EPI = false, bool SP2 = false>
; __device__ __forceinline__ void gemm_phase(PG8_LAS unsigned char* lds, const Gemm g, const Sched& S, const Epi& E) {
;     ...
;             const bool last = (t == nt - 2);
;             const char* a1 = cA + (size_t)(t + 1) * kstep;
;             const char* a2 = last ? nA : cA + (size_t)(t + 2) * kstep; const char* b2 = last ? nB : cB + (size_t)(t + 2) * kstep;
;             const char* a3 = a2 + kstep; const char* b3 = b2 + kstep;
;             if (last && has_next) S.a_ready(nxt);
;             if constexpr (SP2) {
;             PG8_LDB(B0, 0, 0); PG8_LDB(B1, 0, 1); PG8_SCHED; PG8_LDA(At, 0, 0); PG8_STAGE(PG8_SA(1, 1), a1 + hstepA, voffA);
;             PG8_WAIT_V(8); PG8_WAIT_L(0); PG8_BAR; PG8_MMA(0, 0, At, B0); PG8_MMA(0, 1, At, B1); PG8_BAR; PG8_SCHED;
;             PG8_LDA(At, 0, 1); PG8_STAGE(PG8_SB(0, 0), b2, voffB); PG8_STAGE(PG8_SB(0, 1), b2 + hstepB, voffB); PG8_STAGE(PG8_SA(0, 0), a2, voffA);
;             PG8_WAIT_V(8); PG8_WAIT_L(0); PG8_BAR; PG8_MMA(1, 0, At, B0); PG8_MMA(1, 1, At, B1); PG8_BAR; PG8_SCHED;
.LBB0_1211:
	ds_read_b128 v[144:147], v149
	ds_read_b128 v[152:155], v149 offset:1024
	ds_read_b128 v[156:159], v149 offset:2048
	ds_read_b128 v[160:163], v149 offset:3072
	ds_read_b128 v[168:171], v150
	ds_read_b128 v[172:175], v150 offset:1024
	ds_read_b128 v[176:179], v150 offset:2048
	ds_read_b128 v[180:183], v150 offset:3072
	s_add_u32 s4, s30, 0xfff80080
	s_addc_u32 s5, s31, -1
	s_cmp_eq_u32 s58, 28
	s_cselect_b32 s37, s21, s5
	s_cselect_b32 s36, s29, s4
	s_cselect_b32 s35, s19, s57
	s_cselect_b32 s34, s55, s56
	v_lshl_add_u64 v[164:165], s[30:31], 0, v[136:137]
	s_add_i32 m0, s25, 0xc000
	ds_read_b128 v[184:187], v151
	ds_read_b128 v[188:191], v151 offset:1024
	ds_read_b128 v[192:195], v151 offset:2048
	ds_read_b128 v[196:199], v151 offset:3072
	ds_read_b128 v[200:203], v151 offset:4096
	ds_read_b128 v[204:207], v151 offset:5120
	ds_read_b128 v[208:211], v151 offset:6144
	ds_read_b128 v[212:215], v151 offset:7168
	global_load_lds_dwordx4 v[164:165], off
	v_lshl_add_u64 v[164:165], s[30:31], 0, v[138:139]
	s_add_i32 m0, s25, 0xe000
	s_nop 0
	global_load_lds_dwordx4 v[164:165], off
	s_waitcnt vmcnt(8)
	s_waitcnt lgkmcnt(0)
	s_barrier
	s_setprio 1
	v_mfma_f32_16x16x32_bf16 v[124:127], v[144:147], v[184:187], v[124:127]
	v_mfma_f32_16x16x32_bf16 v[120:123], v[156:159], v[184:187], v[120:123]
	v_mfma_f32_16x16x32_bf16 v[108:111], v[144:147], v[192:195], v[108:111]
	v_mfma_f32_16x16x32_bf16 v[104:107], v[156:159], v[192:195], v[104:107]
	v_mfma_f32_16x16x32_bf16 v[92:95], v[144:147], v[200:203], v[92:95]
	v_mfma_f32_16x16x32_bf16 v[88:91], v[156:159], v[200:203], v[88:91]
	v_mfma_f32_16x16x32_bf16 v[76:79], v[144:147], v[208:211], v[76:79]
	v_mfma_f32_16x16x32_bf16 v[72:75], v[156:159], v[208:211], v[72:75]
	v_mfma_f32_16x16x32_bf16 v[124:127], v[152:155], v[188:191], v[124:127]
	v_mfma_f32_16x16x32_bf16 v[120:123], v[160:163], v[188:191], v[120:123]
	v_mfma_f32_16x16x32_bf16 v[108:111], v[152:155], v[196:199], v[108:111]
	v_mfma_f32_16x16x32_bf16 v[104:107], v[160:163], v[196:199], v[104:107]
	v_mfma_f32_16x16x32_bf16 v[92:95], v[152:155], v[204:207], v[92:95]
	v_mfma_f32_16x16x32_bf16 v[88:91], v[160:163], v[204:207], v[88:91]
	v_mfma_f32_16x16x32_bf16 v[76:79], v[152:155], v[212:215], v[76:79]
	v_mfma_f32_16x16x32_bf16 v[72:75], v[160:163], v[212:215], v[72:75]
	v_mfma_f32_16x16x32_bf16 v[116:119], v[168:171], v[184:187], v[116:119]
	v_mfma_f32_16x16x32_bf16 v[112:115], v[176:179], v[184:187], v[112:115]
	v_mfma_f32_16x16x32_bf16 v[100:103], v[168:171], v[192:195], v[100:103]
	v_mfma_f32_16x16x32_bf16 v[96:99], v[176:179], v[192:195], v[96:99]
	v_mfma_f32_16x16x32_bf16 v[84:87], v[168:171], v[200:203], v[84:87]
	v_mfma_f32_16x16x32_bf16 v[80:83], v[176:179], v[200:203], v[80:83]
	v_mfma_f32_16x16x32_bf16 v[68:71], v[168:171], v[208:211], v[68:71]
	v_mfma_f32_16x16x32_bf16 v[64:67], v[176:179], v[208:211], v[64:67]
	v_mfma_f32_16x16x32_bf16 v[116:119], v[172:175], v[188:191], v[116:119]
	v_mfma_f32_16x16x32_bf16 v[112:115], v[180:183], v[188:191], v[112:115]
	v_mfma_f32_16x16x32_bf16 v[100:103], v[172:175], v[196:199], v[100:103]
	v_mfma_f32_16x16x32_bf16 v[96:99], v[180:183], v[196:199], v[96:99]
	v_mfma_f32_16x16x32_bf16 v[84:87], v[172:175], v[204:207], v[84:87]
	v_mfma_f32_16x16x32_bf16 v[80:83], v[180:183], v[204:207], v[80:83]
	v_mfma_f32_16x16x32_bf16 v[68:71], v[172:175], v[212:215], v[68:71]
	v_mfma_f32_16x16x32_bf16 v[64:67], v[180:183], v[212:215], v[64:67]
	s_setprio 0
	s_barrier
	s_add_i32 s4, s44, s47
	v_lshl_add_u64 v[164:165], s[34:35], 0, v[130:131]
	s_mov_b32 m0, s4
	ds_read_b128 v[184:187], v151 offset:16384
	ds_read_b128 v[188:191], v151 offset:17408
	ds_read_b128 v[192:195], v151 offset:18432
	ds_read_b128 v[196:199], v151 offset:19456
	ds_read_b128 v[200:203], v151 offset:20480
	ds_read_b128 v[204:207], v151 offset:21504
	ds_read_b128 v[208:211], v151 offset:22528
	ds_read_b128 v[212:215], v151 offset:23552
	global_load_lds_dwordx4 v[164:165], off
	s_add_i32 m0, s4, 0x2000
	s_add_u32 s4, s34, 0x80000
	v_lshl_add_u64 v[216:217], s[34:35], 0, v[134:135]
	s_addc_u32 s5, s35, 0
	s_add_i32 s59, s45, s47
	global_load_lds_dwordx4 v[216:217], off
	v_lshl_add_u64 v[218:219], s[4:5], 0, v[130:131]
	s_mov_b32 m0, s59
	v_lshl_add_u64 v[220:221], s[36:37], 0, v[132:133]
	global_load_lds_dwordx4 v[218:219], off
	v_lshl_add_u64 v[218:219], s[4:5], 0, v[134:135]
	s_add_i32 m0, s59, 0x2000
	s_nop 0
	global_load_lds_dwordx4 v[218:219], off
	v_lshl_add_u64 v[218:219], s[36:37], 0, v[128:129]
	s_mov_b32 m0, s25
	s_nop 0
	global_load_lds_dwordx4 v[218:219], off
	s_mov_b32 m0, s33
	s_nop 0
	global_load_lds_dwordx4 v[220:221], off
	s_waitcnt vmcnt(8)
	s_waitcnt lgkmcnt(0)
	s_barrier
; #define PG8_STAGE(bufoff, gbase, voff) do { _Pragma("unroll") for (int _i = 0; _i < 2; ++_i) \
;         __builtin_amdgcn_global_load_lds((const unsigned*)((const char*)(gbase) + (voff)[_i]), (PG8_LAS unsigned*)(lds + (bufoff) + ldsw + _i * 8192), 16, 0, 0); } while (0)
; #define PG8_LDA(dst, b, h) do { _Pragma("unroll") for (int m = 0; m < 4; ++m) _Pragma("unroll") for (int k = 0; k < 2; ++k) dst[m][k] = *(const PG8_LAS bf16x8*)(lds + PG8_SA(b, h) + aoff + m * 2048 + k * 1024); } while (0)
; #define PG8_LDB(dst, b, h) do { _Pragma("unroll") for (int n = 0; n < 2; ++n) _Pragma("unroll") for (int k = 0; k < 2; ++k) dst[n][k] = *(const PG8_LAS bf16x8*)(lds + PG8_SB(b, h) + boff + n * 2048 + k * 1024); } while (0)
; #define PG8_MMA(ai, bj, At, Bt) do { __builtin_amdgcn_s_setprio(1); _Pragma("unroll") for (int m = 0; m < 4; ++m) _Pragma("unroll") for (int n = 0; n < 2; ++n) _Pragma("unroll") for (int k = 0; k < 2; ++k) \
;         acc[ai][bj][m][n] = __builtin_amdgcn_mfma_f32_16x16x32_bf16(Bt[n][k], At[m][k], acc[ai][bj][m][n], 0, 0, 0); __builtin_amdgcn_s_setprio(0); } while (0)
; #define PG8_WAIT_V(n) asm volatile("s_waitcnt vmcnt(" #n ")" ::: "memory")
; #define PG8_WAIT_L(n) asm volatile("s_waitcnt lgkmcnt(" #n ")" ::: "memory")
; #define PG8_BAR __builtin_amdgcn_s_barrier()
; #define PG8_SCHED __builtin_amdgcn_sched_barrier(0)
; template <class Epi, class Sched, bool ALIGN_EPI = false, bool SP2 = false>
; __device__ __forceinline__ void gemm_phase(PG8_LAS unsigned char* lds, const Gemm g, const Sched& S, const Epi& E) {
;     ...
;             PG8_WAIT_V(8); PG8_WAIT_L(0); PG8_BAR; PG8_MMA(1, 0, At, B0); PG8_MMA(1, 1, At, B1); PG8_BAR; PG8_SCHED;
;             PG8_LDB(B0, 1, 0); PG8_LDB(B1, 1, 1); PG8_SCHED; PG8_LDA(At, 1, 0); PG8_STAGE(PG8_SA(0, 1), a2 + hstepA, voffA);
;             PG8_WAIT_V(8); PG8_WAIT_L(0); PG8_BAR; PG8_MMA(0, 0, At, B0); PG8_MMA(0, 1, At, B1); PG8_BAR; PG8_SCHED;
	s_setprio 1
	v_mfma_f32_16x16x32_bf16 v[60:63], v[144:147], v[184:187], v[60:63]
	v_mfma_f32_16x16x32_bf16 v[56:59], v[156:159], v[184:187], v[56:59]
	v_mfma_f32_16x16x32_bf16 v[44:47], v[144:147], v[192:195], v[44:47]
	v_mfma_f32_16x16x32_bf16 v[40:43], v[156:159], v[192:195], v[40:43]
	v_mfma_f32_16x16x32_bf16 v[28:31], v[144:147], v[200:203], v[28:31]
	v_mfma_f32_16x16x32_bf16 v[24:27], v[156:159], v[200:203], v[24:27]
	v_mfma_f32_16x16x32_bf16 v[12:15], v[144:147], v[208:211], v[12:15]
	v_mfma_f32_16x16x32_bf16 v[8:11], v[156:159], v[208:211], v[8:11]
	v_mfma_f32_16x16x32_bf16 v[60:63], v[152:155], v[188:191], v[60:63]
	v_mfma_f32_16x16x32_bf16 v[56:59], v[160:163], v[188:191], v[56:59]
	v_mfma_f32_16x16x32_bf16 v[44:47], v[152:155], v[196:199], v[44:47]
	v_mfma_f32_16x16x32_bf16 v[40:43], v[160:163], v[196:199], v[40:43]
	v_mfma_f32_16x16x32_bf16 v[28:31], v[152:155], v[204:207], v[28:31]
	v_mfma_f32_16x16x32_bf16 v[24:27], v[160:163], v[204:207], v[24:27]
	v_mfma_f32_16x16x32_bf16 v[12:15], v[152:155], v[212:215], v[12:15]
	v_mfma_f32_16x16x32_bf16 v[8:11], v[160:163], v[212:215], v[8:11]
	v_mfma_f32_16x16x32_bf16 v[52:55], v[168:171], v[184:187], v[52:55]
	v_mfma_f32_16x16x32_bf16 v[48:51], v[176:179], v[184:187], v[48:51]
	v_mfma_f32_16x16x32_bf16 v[36:39], v[168:171], v[192:195], v[36:39]
	v_mfma_f32_16x16x32_bf16 v[32:35], v[176:179], v[192:195], v[32:35]
	v_mfma_f32_16x16x32_bf16 v[20:23], v[168:171], v[200:203], v[20:23]
	v_mfma_f32_16x16x32_bf16 v[16:19], v[176:179], v[200:203], v[16:19]
	v_mfma_f32_16x16x32_bf16 v[4:7], v[168:171], v[208:211], v[4:7]
	v_mfma_f32_16x16x32_bf16 v[0:3], v[176:179], v[208:211], v[0:3]
	v_mfma_f32_16x16x32_bf16 v[52:55], v[172:175], v[188:191], v[52:55]
	v_mfma_f32_16x16x32_bf16 v[48:51], v[180:183], v[188:191], v[48:51]
	v_mfma_f32_16x16x32_bf16 v[36:39], v[172:175], v[196:199], v[36:39]
	v_mfma_f32_16x16x32_bf16 v[32:35], v[180:183], v[196:199], v[32:35]
	v_mfma_f32_16x16x32_bf16 v[20:23], v[172:175], v[204:207], v[20:23]
	v_mfma_f32_16x16x32_bf16 v[16:19], v[180:183], v[204:207], v[16:19]
	v_mfma_f32_16x16x32_bf16 v[4:7], v[172:175], v[212:215], v[4:7]
	v_mfma_f32_16x16x32_bf16 v[0:3], v[180:183], v[212:215], v[0:3]
	s_setprio 0
	s_barrier
	s_add_i32 s59, 0, 0x18000
	s_add_i32 s60, 0, 0x1c000
	v_add_u32_e32 v160, s59, v148
	v_add_u32_e32 v166, s60, v148
	ds_read_b128 v[144:147], v160
	ds_read_b128 v[152:155], v160 offset:1024
	ds_read_b128 v[156:159], v160 offset:2048
	ds_read_b128 v[160:163], v160 offset:3072
	ds_read_b128 v[168:171], v166
	ds_read_b128 v[172:175], v166 offset:1024
	ds_read_b128 v[176:179], v166 offset:2048
	ds_read_b128 v[180:183], v166 offset:3072
	s_add_u32 s4, s36, 0x80000
	s_addc_u32 s5, s37, 0
	s_mov_b32 m0, s38
	v_lshl_add_u64 v[222:223], s[4:5], 0, v[128:129]
	ds_read_b128 v[184:187], v151 offset:32768
	ds_read_b128 v[188:191], v151 offset:33792
	ds_read_b128 v[192:195], v151 offset:34816
	ds_read_b128 v[196:199], v151 offset:35840
	ds_read_b128 v[200:203], v151 offset:36864
	ds_read_b128 v[204:207], v151 offset:37888
	ds_read_b128 v[208:211], v151 offset:38912
	ds_read_b128 v[212:215], v151 offset:39936
	global_load_lds_dwordx4 v[222:223], off
	v_lshl_add_u64 v[222:223], s[4:5], 0, v[132:133]
	s_mov_b32 m0, s39
	s_nop 0
	global_load_lds_dwordx4 v[222:223], off
	s_waitcnt vmcnt(8)
	s_waitcnt lgkmcnt(0)
	s_barrier
	s_setprio 1
	v_mfma_f32_16x16x32_bf16 v[124:127], v[144:147], v[184:187], v[124:127]
	v_mfma_f32_16x16x32_bf16 v[120:123], v[156:159], v[184:187], v[120:123]
	v_mfma_f32_16x16x32_bf16 v[108:111], v[144:147], v[192:195], v[108:111]
	v_mfma_f32_16x16x32_bf16 v[104:107], v[156:159], v[192:195], v[104:107]
	v_mfma_f32_16x16x32_bf16 v[92:95], v[144:147], v[200:203], v[92:95]
	v_mfma_f32_16x16x32_bf16 v[88:91], v[156:159], v[200:203], v[88:91]
	v_mfma_f32_16x16x32_bf16 v[76:79], v[144:147], v[208:211], v[76:79]
	v_mfma_f32_16x16x32_bf16 v[72:75], v[156:159], v[208:211], v[72:75]
	v_mfma_f32_16x16x32_bf16 v[124:127], v[152:155], v[188:191], v[124:127]
	v_mfma_f32_16x16x32_bf16 v[120:123], v[160:163], v[188:191], v[120:123]
	v_mfma_f32_16x16x32_bf16 v[108:111], v[152:155], v[196:199], v[108:111]
	v_mfma_f32_16x16x32_bf16 v[104:107], v[160:163], v[196:199], v[104:107]
	v_mfma_f32_16x16x32_bf16 v[92:95], v[152:155], v[204:207], v[92:95]
	v_mfma_f32_16x16x32_bf16 v[88:91], v[160:163], v[204:207], v[88:91]
	v_mfma_f32_16x16x32_bf16 v[76:79], v[152:155], v[212:215], v[76:79]
	v_mfma_f32_16x16x32_bf16 v[72:75], v[160:163], v[212:215], v[72:75]
	v_mfma_f32_16x16x32_bf16 v[116:119], v[168:171], v[184:187], v[116:119]
	v_mfma_f32_16x16x32_bf16 v[112:115], v[176:179], v[184:187], v[112:115]
	v_mfma_f32_16x16x32_bf16 v[100:103], v[168:171], v[192:195], v[100:103]
	v_mfma_f32_16x16x32_bf16 v[96:99], v[176:179], v[192:195], v[96:99]
	v_mfma_f32_16x16x32_bf16 v[84:87], v[168:171], v[200:203], v[84:87]
	v_mfma_f32_16x16x32_bf16 v[80:83], v[176:179], v[200:203], v[80:83]
	v_mfma_f32_16x16x32_bf16 v[68:71], v[168:171], v[208:211], v[68:71]
	v_mfma_f32_16x16x32_bf16 v[64:67], v[176:179], v[208:211], v[64:67]
	v_mfma_f32_16x16x32_bf16 v[116:119], v[172:175], v[188:191], v[116:119]
	v_mfma_f32_16x16x32_bf16 v[112:115], v[180:183], v[188:191], v[112:115]
	v_mfma_f32_16x16x32_bf16 v[100:103], v[172:175], v[196:199], v[100:103]
	v_mfma_f32_16x16x32_bf16 v[96:99], v[180:183], v[196:199], v[96:99]
	v_mfma_f32_16x16x32_bf16 v[84:87], v[172:175], v[204:207], v[84:87]
	v_mfma_f32_16x16x32_bf16 v[80:83], v[180:183], v[204:207], v[80:83]
	v_mfma_f32_16x16x32_bf16 v[68:71], v[172:175], v[212:215], v[68:71]
	v_mfma_f32_16x16x32_bf16 v[64:67], v[180:183], v[212:215], v[64:67]
	s_setprio 0
	s_barrier
; #define PG8_STAGE(bufoff, gbase, voff) do { _Pragma("unroll") for (int _i = 0; _i < 2; ++_i) \
;         __builtin_amdgcn_global_load_lds((const unsigned*)((const char*)(gbase) + (voff)[_i]), (PG8_LAS unsigned*)(lds + (bufoff) + ldsw + _i * 8192), 16, 0, 0); } while (0)
; #define PG8_LDA(dst, b, h) do { _Pragma("unroll") for (int m = 0; m < 4; ++m) _Pragma("unroll") for (int k = 0; k < 2; ++k) dst[m][k] = *(const PG8_LAS bf16x8*)(lds + PG8_SA(b, h) + aoff + m * 2048 + k * 1024); } while (0)
; #define PG8_MMA(ai, bj, At, Bt) do { __builtin_amdgcn_s_setprio(1); _Pragma("unroll") for (int m = 0; m < 4; ++m) _Pragma("unroll") for (int n = 0; n < 2; ++n) _Pragma("unroll") for (int k = 0; k < 2; ++k) \
;         acc[ai][bj][m][n] = __builtin_amdgcn_mfma_f32_16x16x32_bf16(Bt[n][k], At[m][k], acc[ai][bj][m][n], 0, 0, 0); __builtin_amdgcn_s_setprio(0); } while (0)
; #define PG8_WAIT_V(n) asm volatile("s_waitcnt vmcnt(" #n ")" ::: "memory")
; #define PG8_WAIT_L(n) asm volatile("s_waitcnt lgkmcnt(" #n ")" ::: "memory")
; #define PG8_BAR __builtin_amdgcn_s_barrier()
; #define PG8_SCHED __builtin_amdgcn_sched_barrier(0)
; template <class Epi, class Sched, bool ALIGN_EPI = false, bool SP2 = false>
; __device__ __forceinline__ void gemm_phase(PG8_LAS unsigned char* lds, const Gemm g, const Sched& S, const Epi& E) {
;     ...
;         for (int t = 0; t < nt; t += 2) {
;     ...
;             PG8_LDA(At, 1, 1); PG8_STAGE(PG8_SB(1, 0), b3, voffB); PG8_STAGE(PG8_SB(1, 1), b3 + hstepB, voffB); PG8_STAGE(PG8_SA(1, 0), a3, voffA);
;             PG8_WAIT_V(8); PG8_WAIT_L(0); PG8_BAR; PG8_MMA(1, 0, At, B0); PG8_MMA(1, 1, At, B1); PG8_BAR; PG8_SCHED;
	s_add_i32 s4, s59, s47
	v_lshl_add_u64 v[164:165], v[164:165], 0, s[16:17]
	s_mov_b32 m0, s4
	ds_read_b128 v[184:187], v151 offset:49152
	ds_read_b128 v[188:191], v151 offset:50176
	ds_read_b128 v[192:195], v151 offset:51200
	ds_read_b128 v[196:199], v151 offset:52224
	ds_read_b128 v[200:203], v151 offset:53248
	ds_read_b128 v[204:207], v151 offset:54272
	ds_read_b128 v[208:211], v151 offset:55296
	ds_read_b128 v[212:215], v151 offset:56320
	global_load_lds_dwordx4 v[164:165], off
	s_add_i32 m0, s4, 0x2000
	s_add_u32 s4, s34, 0x80080
	v_lshl_add_u64 v[164:165], v[216:217], 0, s[16:17]
	s_addc_u32 s5, s35, 0
	s_add_i32 s34, s60, s47
	global_load_lds_dwordx4 v[164:165], off
	v_lshl_add_u64 v[164:165], s[4:5], 0, v[130:131]
	s_mov_b32 m0, s34
	s_nop 0
	global_load_lds_dwordx4 v[164:165], off
	v_lshl_add_u64 v[164:165], s[4:5], 0, v[134:135]
	s_add_i32 m0, s34, 0x2000
	s_nop 0
	global_load_lds_dwordx4 v[164:165], off
	v_lshl_add_u64 v[164:165], v[218:219], 0, s[16:17]
	s_mov_b32 m0, s40
	s_nop 0
	global_load_lds_dwordx4 v[164:165], off
	v_lshl_add_u64 v[164:165], v[220:221], 0, s[16:17]
	s_mov_b32 m0, s41
	s_nop 0
	global_load_lds_dwordx4 v[164:165], off
	s_waitcnt vmcnt(8)
	s_waitcnt lgkmcnt(0)
	s_barrier
	s_setprio 1
	v_mfma_f32_16x16x32_bf16 v[60:63], v[144:147], v[184:187], v[60:63]
	v_mfma_f32_16x16x32_bf16 v[56:59], v[156:159], v[184:187], v[56:59]
	v_mfma_f32_16x16x32_bf16 v[44:47], v[144:147], v[192:195], v[44:47]
	v_mfma_f32_16x16x32_bf16 v[40:43], v[156:159], v[192:195], v[40:43]
	v_mfma_f32_16x16x32_bf16 v[28:31], v[144:147], v[200:203], v[28:31]
	v_mfma_f32_16x16x32_bf16 v[24:27], v[156:159], v[200:203], v[24:27]
	v_mfma_f32_16x16x32_bf16 v[12:15], v[144:147], v[208:211], v[12:15]
	v_mfma_f32_16x16x32_bf16 v[8:11], v[156:159], v[208:211], v[8:11]
	v_mfma_f32_16x16x32_bf16 v[60:63], v[152:155], v[188:191], v[60:63]
	v_mfma_f32_16x16x32_bf16 v[56:59], v[160:163], v[188:191], v[56:59]
	v_mfma_f32_16x16x32_bf16 v[44:47], v[152:155], v[196:199], v[44:47]
	v_mfma_f32_16x16x32_bf16 v[40:43], v[160:163], v[196:199], v[40:43]
	v_mfma_f32_16x16x32_bf16 v[28:31], v[152:155], v[204:207], v[28:31]
	v_mfma_f32_16x16x32_bf16 v[24:27], v[160:163], v[204:207], v[24:27]
	v_mfma_f32_16x16x32_bf16 v[12:15], v[152:155], v[212:215], v[12:15]
	v_mfma_f32_16x16x32_bf16 v[8:11], v[160:163], v[212:215], v[8:11]
	v_mfma_f32_16x16x32_bf16 v[52:55], v[168:171], v[184:187], v[52:55]
	v_mfma_f32_16x16x32_bf16 v[48:51], v[176:179], v[184:187], v[48:51]
	v_mfma_f32_16x16x32_bf16 v[36:39], v[168:171], v[192:195], v[36:39]
	v_mfma_f32_16x16x32_bf16 v[32:35], v[176:179], v[192:195], v[32:35]
	v_mfma_f32_16x16x32_bf16 v[20:23], v[168:171], v[200:203], v[20:23]
	v_mfma_f32_16x16x32_bf16 v[16:19], v[176:179], v[200:203], v[16:19]
	v_mfma_f32_16x16x32_bf16 v[4:7], v[168:171], v[208:211], v[4:7]
	v_mfma_f32_16x16x32_bf16 v[0:3], v[176:179], v[208:211], v[0:3]
	v_mfma_f32_16x16x32_bf16 v[52:55], v[172:175], v[188:191], v[52:55]
	v_mfma_f32_16x16x32_bf16 v[48:51], v[180:183], v[188:191], v[48:51]
	v_mfma_f32_16x16x32_bf16 v[36:39], v[172:175], v[196:199], v[36:39]
	v_mfma_f32_16x16x32_bf16 v[32:35], v[180:183], v[196:199], v[32:35]
	v_mfma_f32_16x16x32_bf16 v[20:23], v[172:175], v[204:207], v[20:23]
	v_mfma_f32_16x16x32_bf16 v[16:19], v[180:183], v[204:207], v[16:19]
	v_mfma_f32_16x16x32_bf16 v[4:7], v[172:175], v[212:215], v[4:7]
	v_mfma_f32_16x16x32_bf16 v[0:3], v[180:183], v[212:215], v[0:3]
	s_add_i32 s58, s58, 2
	s_add_u32 s30, s30, 0x100
	s_addc_u32 s31, s31, 0
	s_add_u32 s56, s56, 0x100
	s_addc_u32 s57, s57, 0
	s_cmp_gt_u32 s58, 29
	s_setprio 0
	s_barrier
	s_cbranch_scc0 .LBB0_1211
	s_and_b64 vcc, exec, s[48:49]
	s_cbranch_vccz .LBB0_1214
	s_barrier

; #define PG8_STAGE(bufoff, gbase, voff) do { _Pragma("unroll") for (int _i = 0; _i < 2; ++_i) \
;         __builtin_amdgcn_global_load_lds((const unsigned*)((const char*)(gbase) + (voff)[_i]), (PG8_LAS unsigned*)(lds + (bufoff) + ldsw + _i * 8192), 16, 0, 0); } while (0)
; #define PG8_LDA(dst, b, h) do { _Pragma("unroll") for (int m = 0; m < 4; ++m) _Pragma("unroll") for (int k = 0; k < 2; ++k) dst[m][k] = *(const PG8_LAS bf16x8*)(lds + PG8_SA(b, h) + aoff + m * 2048 + k * 1024); } while (0)
; #define PG8_LDB(dst, b, h) do { _Pragma("unroll") for (int n = 0; n < 2; ++n) _Pragma("unroll") for (int k = 0; k < 2; ++k) dst[n][k] = *(const PG8_LAS bf16x8*)(lds + PG8_SB(b, h) + boff + n * 2048 + k * 1024); } while (0)
; #define PG8_MMA(ai, bj, At, Bt) do { __builtin_amdgcn_s_setprio(1); _Pragma("unroll") for (int m = 0; m < 4; ++m) _Pragma("unroll") for (int n = 0; n < 2; ++n) _Pragma("unroll") for (int k = 0; k < 2; ++k) \
;         acc[ai][bj][m][n] = __builtin_amdgcn_mfma_f32_16x16x32_bf16(Bt[n][k], At[m][k], acc[ai][bj][m][n], 0, 0, 0); __builtin_amdgcn_s_setprio(0); } while (0)
; #define PG8_WAIT_V(n) asm volatile("s_waitcnt vmcnt(" #n ")" ::: "memory")
; #define PG8_WAIT_L(n) asm volatile("s_waitcnt lgkmcnt(" #n ")" ::: "memory")
; template <class Epi, class Sched, bool ALIGN_EPI = false, bool SP2 = false>
; __device__ __forceinline__ void gemm_phase(PG8_LAS unsigned char* lds, const Gemm g, const Sched& S, const Epi& E) {
;     ...
;             const bool last = (t == nt - 2);
;             const char* a1 = cA + (size_t)(t + 1) * kstep;
;             const char* a2 = last ? nA : cA + (size_t)(t + 2) * kstep; const char* b2 = last ? nB : cB + (size_t)(t + 2) * kstep;
;             const char* a3 = a2 + kstep; const char* b3 = b2 + kstep;
;             if (last && has_next) S.a_ready(nxt);
;             if constexpr (SP2) {
;             PG8_LDB(B0, 0, 0); PG8_LDB(B1, 0, 1); PG8_SCHED; PG8_LDA(At, 0, 0); PG8_STAGE(PG8_SA(1, 1), a1 + hstepA, voffA);
;             PG8_WAIT_V(8); PG8_WAIT_L(0); PG8_BAR; PG8_MMA(0, 0, At, B0); PG8_MMA(0, 1, At, B1); PG8_BAR; PG8_SCHED;
;             PG8_LDA(At, 0, 1); PG8_STAGE(PG8_SB(0, 0), b2, voffB); PG8_STAGE(PG8_SB(0, 1), b2 + hstepB, voffB); PG8_STAGE(PG8_SA(0, 0), a2, voffA);
;             PG8_WAIT_V(8); PG8_WAIT_L(0); PG8_BAR; PG8_MMA(1, 0, At, B0); PG8_MMA(1, 1, At, B1); PG8_BAR; PG8_SCHED;
.LBB0_1287:
	ds_read_b128 v[144:147], v149
	ds_read_b128 v[154:157], v149 offset:1024
	ds_read_b128 v[158:161], v149 offset:2048
	ds_read_b128 v[162:165], v149 offset:3072
	ds_read_b128 v[168:171], v150
	ds_read_b128 v[172:175], v150 offset:1024
	ds_read_b128 v[176:179], v150 offset:2048
	ds_read_b128 v[180:183], v150 offset:3072
	s_add_u32 s4, s28, 0xfff80080
	s_addc_u32 s5, s29, -1
	s_cmp_eq_u32 s58, 28
	s_cselect_b32 s35, s19, s5
	s_cselect_b32 s34, s54, s4
	s_cselect_b32 s31, s17, s57
	s_cselect_b32 s30, s55, s56
	v_lshl_add_u64 v[216:217], s[28:29], 0, v[136:137]
	s_add_i32 m0, s27, 0xc000
	ds_read_b128 v[184:187], v151
	ds_read_b128 v[188:191], v151 offset:1024
	ds_read_b128 v[192:195], v151 offset:2048
	ds_read_b128 v[196:199], v151 offset:3072
	ds_read_b128 v[200:203], v151 offset:4096
	ds_read_b128 v[204:207], v151 offset:5120
	ds_read_b128 v[208:211], v151 offset:6144
	ds_read_b128 v[212:215], v151 offset:7168
	global_load_lds_dwordx4 v[216:217], off
	v_lshl_add_u64 v[216:217], s[28:29], 0, v[138:139]
	s_add_i32 m0, s27, 0xe000
	s_nop 0
	global_load_lds_dwordx4 v[216:217], off
	s_waitcnt vmcnt(8)
	s_waitcnt lgkmcnt(0)
	s_barrier
	s_setprio 1
	v_mfma_f32_16x16x32_bf16 v[116:119], v[144:147], v[184:187], v[116:119]
	v_mfma_f32_16x16x32_bf16 v[112:115], v[158:161], v[184:187], v[112:115]
	v_mfma_f32_16x16x32_bf16 v[100:103], v[144:147], v[192:195], v[100:103]
	v_mfma_f32_16x16x32_bf16 v[96:99], v[158:161], v[192:195], v[96:99]
	v_mfma_f32_16x16x32_bf16 v[84:87], v[144:147], v[200:203], v[84:87]
	v_mfma_f32_16x16x32_bf16 v[80:83], v[158:161], v[200:203], v[80:83]
	v_mfma_f32_16x16x32_bf16 v[68:71], v[144:147], v[208:211], v[68:71]
	v_mfma_f32_16x16x32_bf16 v[64:67], v[158:161], v[208:211], v[64:67]
	v_mfma_f32_16x16x32_bf16 v[116:119], v[154:157], v[188:191], v[116:119]
	v_mfma_f32_16x16x32_bf16 v[112:115], v[162:165], v[188:191], v[112:115]
	v_mfma_f32_16x16x32_bf16 v[100:103], v[154:157], v[196:199], v[100:103]
	v_mfma_f32_16x16x32_bf16 v[96:99], v[162:165], v[196:199], v[96:99]
	v_mfma_f32_16x16x32_bf16 v[84:87], v[154:157], v[204:207], v[84:87]
	v_mfma_f32_16x16x32_bf16 v[80:83], v[162:165], v[204:207], v[80:83]
	v_mfma_f32_16x16x32_bf16 v[68:71], v[154:157], v[212:215], v[68:71]
	v_mfma_f32_16x16x32_bf16 v[64:67], v[162:165], v[212:215], v[64:67]
	v_mfma_f32_16x16x32_bf16 v[124:127], v[168:171], v[184:187], v[124:127]
	v_mfma_f32_16x16x32_bf16 v[120:123], v[176:179], v[184:187], v[120:123]
	v_mfma_f32_16x16x32_bf16 v[108:111], v[168:171], v[192:195], v[108:111]
	v_mfma_f32_16x16x32_bf16 v[104:107], v[176:179], v[192:195], v[104:107]
	v_mfma_f32_16x16x32_bf16 v[92:95], v[168:171], v[200:203], v[92:95]
	v_mfma_f32_16x16x32_bf16 v[88:91], v[176:179], v[200:203], v[88:91]
	v_mfma_f32_16x16x32_bf16 v[76:79], v[168:171], v[208:211], v[76:79]
	v_mfma_f32_16x16x32_bf16 v[72:75], v[176:179], v[208:211], v[72:75]
	v_mfma_f32_16x16x32_bf16 v[124:127], v[172:175], v[188:191], v[124:127]
	v_mfma_f32_16x16x32_bf16 v[120:123], v[180:183], v[188:191], v[120:123]
	v_mfma_f32_16x16x32_bf16 v[108:111], v[172:175], v[196:199], v[108:111]
	v_mfma_f32_16x16x32_bf16 v[104:107], v[180:183], v[196:199], v[104:107]
	v_mfma_f32_16x16x32_bf16 v[92:95], v[172:175], v[204:207], v[92:95]
	v_mfma_f32_16x16x32_bf16 v[88:91], v[180:183], v[204:207], v[88:91]
	v_mfma_f32_16x16x32_bf16 v[76:79], v[172:175], v[212:215], v[76:79]
	v_mfma_f32_16x16x32_bf16 v[72:75], v[180:183], v[212:215], v[72:75]
	s_setprio 0
	s_barrier
	s_add_i32 s4, s41, s47
	v_lshl_add_u64 v[216:217], s[30:31], 0, v[132:133]
	s_mov_b32 m0, s4
	ds_read_b128 v[184:187], v151 offset:16384
	ds_read_b128 v[188:191], v151 offset:17408
	ds_read_b128 v[192:195], v151 offset:18432
	ds_read_b128 v[196:199], v151 offset:19456
	ds_read_b128 v[200:203], v151 offset:20480
	ds_read_b128 v[204:207], v151 offset:21504
	ds_read_b128 v[208:211], v151 offset:22528
	ds_read_b128 v[212:215], v151 offset:23552
	global_load_lds_dwordx4 v[216:217], off
	s_add_i32 m0, s4, 0x2000
	s_add_u32 s4, s30, 0x80000
	v_lshl_add_u64 v[218:219], s[30:31], 0, v[128:129]
	s_addc_u32 s5, s31, 0
	s_add_i32 s59, s44, s47
	global_load_lds_dwordx4 v[218:219], off
	v_lshl_add_u64 v[220:221], s[4:5], 0, v[132:133]
	s_mov_b32 m0, s59
	v_lshl_add_u64 v[222:223], s[34:35], 0, v[130:131]
	global_load_lds_dwordx4 v[220:221], off
	v_lshl_add_u64 v[220:221], s[4:5], 0, v[128:129]
	s_add_i32 m0, s59, 0x2000
	s_nop 0
	global_load_lds_dwordx4 v[220:221], off
	v_lshl_add_u64 v[220:221], s[34:35], 0, v[134:135]
	s_mov_b32 m0, s27
	s_nop 0
	global_load_lds_dwordx4 v[220:221], off
	s_mov_b32 m0, s33
	s_nop 0
	global_load_lds_dwordx4 v[222:223], off
	s_waitcnt vmcnt(8)
	s_waitcnt lgkmcnt(0)
	s_barrier
; #define PG8_STAGE(bufoff, gbase, voff) do { _Pragma("unroll") for (int _i = 0; _i < 2; ++_i) \
;         __builtin_amdgcn_global_load_lds((const unsigned*)((const char*)(gbase) + (voff)[_i]), (PG8_LAS unsigned*)(lds + (bufoff) + ldsw + _i * 8192), 16, 0, 0); } while (0)
; #define PG8_LDA(dst, b, h) do { _Pragma("unroll") for (int m = 0; m < 4; ++m) _Pragma("unroll") for (int k = 0; k < 2; ++k) dst[m][k] = *(const PG8_LAS bf16x8*)(lds + PG8_SA(b, h) + aoff + m * 2048 + k * 1024); } while (0)
; #define PG8_LDB(dst, b, h) do { _Pragma("unroll") for (int n = 0; n < 2; ++n) _Pragma("unroll") for (int k = 0; k < 2; ++k) dst[n][k] = *(const PG8_LAS bf16x8*)(lds + PG8_SB(b, h) + boff + n * 2048 + k * 1024); } while (0)
; #define PG8_MMA(ai, bj, At, Bt) do { __builtin_amdgcn_s_setprio(1); _Pragma("unroll") for (int m = 0; m < 4; ++m) _Pragma("unroll") for (int n = 0; n < 2; ++n) _Pragma("unroll") for (int k = 0; k < 2; ++k) \
;         acc[ai][bj][m][n] = __builtin_amdgcn_mfma_f32_16x16x32_bf16(Bt[n][k], At[m][k], acc[ai][bj][m][n], 0, 0, 0); __builtin_amdgcn_s_setprio(0); } while (0)
; #define PG8_WAIT_V(n) asm volatile("s_waitcnt vmcnt(" #n ")" ::: "memory")
; #define PG8_WAIT_L(n) asm volatile("s_waitcnt lgkmcnt(" #n ")" ::: "memory")
; #define PG8_BAR __builtin_amdgcn_s_barrier()
; #define PG8_SCHED __builtin_amdgcn_sched_barrier(0)
; template <class Epi, class Sched, bool ALIGN_EPI = false, bool SP2 = false>
; __device__ __forceinline__ void gemm_phase(PG8_LAS unsigned char* lds, const Gemm g, const Sched& S, const Epi& E) {
;     ...
;             PG8_WAIT_V(8); PG8_WAIT_L(0); PG8_BAR; PG8_MMA(1, 0, At, B0); PG8_MMA(1, 1, At, B1); PG8_BAR; PG8_SCHED;
;             PG8_LDB(B0, 1, 0); PG8_LDB(B1, 1, 1); PG8_SCHED; PG8_LDA(At, 1, 0); PG8_STAGE(PG8_SA(0, 1), a2 + hstepA, voffA);
;             PG8_WAIT_V(8); PG8_WAIT_L(0); PG8_BAR; PG8_MMA(0, 0, At, B0); PG8_MMA(0, 1, At, B1); PG8_BAR; PG8_SCHED;
	s_setprio 1
	v_mfma_f32_16x16x32_bf16 v[52:55], v[144:147], v[184:187], v[52:55]
	v_mfma_f32_16x16x32_bf16 v[48:51], v[158:161], v[184:187], v[48:51]
	v_mfma_f32_16x16x32_bf16 v[36:39], v[144:147], v[192:195], v[36:39]
	v_mfma_f32_16x16x32_bf16 v[32:35], v[158:161], v[192:195], v[32:35]
	v_mfma_f32_16x16x32_bf16 v[20:23], v[144:147], v[200:203], v[20:23]
	v_mfma_f32_16x16x32_bf16 v[16:19], v[158:161], v[200:203], v[16:19]
	v_mfma_f32_16x16x32_bf16 v[8:11], v[144:147], v[208:211], v[8:11]
	v_mfma_f32_16x16x32_bf16 v[4:7], v[158:161], v[208:211], v[4:7]
	v_mfma_f32_16x16x32_bf16 v[52:55], v[154:157], v[188:191], v[52:55]
	v_mfma_f32_16x16x32_bf16 v[48:51], v[162:165], v[188:191], v[48:51]
	v_mfma_f32_16x16x32_bf16 v[36:39], v[154:157], v[196:199], v[36:39]
	v_mfma_f32_16x16x32_bf16 v[32:35], v[162:165], v[196:199], v[32:35]
	v_mfma_f32_16x16x32_bf16 v[20:23], v[154:157], v[204:207], v[20:23]
	v_mfma_f32_16x16x32_bf16 v[16:19], v[162:165], v[204:207], v[16:19]
	v_mfma_f32_16x16x32_bf16 v[8:11], v[154:157], v[212:215], v[8:11]
	v_mfma_f32_16x16x32_bf16 v[4:7], v[162:165], v[212:215], v[4:7]
	v_mfma_f32_16x16x32_bf16 v[60:63], v[168:171], v[184:187], v[60:63]
	v_mfma_f32_16x16x32_bf16 v[56:59], v[176:179], v[184:187], v[56:59]
	v_mfma_f32_16x16x32_bf16 v[44:47], v[168:171], v[192:195], v[44:47]
	v_mfma_f32_16x16x32_bf16 v[40:43], v[176:179], v[192:195], v[40:43]
	v_mfma_f32_16x16x32_bf16 v[28:31], v[168:171], v[200:203], v[28:31]
	v_mfma_f32_16x16x32_bf16 v[24:27], v[176:179], v[200:203], v[24:27]
	v_mfma_f32_16x16x32_bf16 v[12:15], v[168:171], v[208:211], v[12:15]
	v_mfma_f32_16x16x32_bf16 v[0:3], v[176:179], v[208:211], v[0:3]
	v_mfma_f32_16x16x32_bf16 v[60:63], v[172:175], v[188:191], v[60:63]
	v_mfma_f32_16x16x32_bf16 v[56:59], v[180:183], v[188:191], v[56:59]
	v_mfma_f32_16x16x32_bf16 v[44:47], v[172:175], v[196:199], v[44:47]
	v_mfma_f32_16x16x32_bf16 v[40:43], v[180:183], v[196:199], v[40:43]
	v_mfma_f32_16x16x32_bf16 v[28:31], v[172:175], v[204:207], v[28:31]
	v_mfma_f32_16x16x32_bf16 v[24:27], v[180:183], v[204:207], v[24:27]
	v_mfma_f32_16x16x32_bf16 v[12:15], v[172:175], v[212:215], v[12:15]
	v_mfma_f32_16x16x32_bf16 v[0:3], v[180:183], v[212:215], v[0:3]
	s_setprio 0
	s_barrier
	s_add_i32 s59, 0, 0x18000
	v_add_u32_e32 v153, s59, v148
	s_add_i32 s60, 0, 0x1c000
	ds_read_b128 v[144:147], v153
	ds_read_b128 v[154:157], v153 offset:1024
	ds_read_b128 v[158:161], v153 offset:2048
	ds_read_b128 v[162:165], v153 offset:3072
	v_add_u32_e32 v153, s60, v148
	ds_read_b128 v[168:171], v153
	ds_read_b128 v[172:175], v153 offset:1024
	ds_read_b128 v[176:179], v153 offset:2048
	ds_read_b128 v[180:183], v153 offset:3072
	s_add_u32 s4, s34, 0x80000
	s_addc_u32 s5, s35, 0
	s_mov_b32 m0, s36
	v_lshl_add_u64 v[224:225], s[4:5], 0, v[134:135]
	ds_read_b128 v[184:187], v151 offset:32768
	ds_read_b128 v[188:191], v151 offset:33792
	ds_read_b128 v[192:195], v151 offset:34816
	ds_read_b128 v[196:199], v151 offset:35840
	ds_read_b128 v[200:203], v151 offset:36864
	ds_read_b128 v[204:207], v151 offset:37888
	ds_read_b128 v[208:211], v151 offset:38912
	ds_read_b128 v[212:215], v151 offset:39936
	global_load_lds_dwordx4 v[224:225], off
	v_lshl_add_u64 v[224:225], s[4:5], 0, v[130:131]
	s_mov_b32 m0, s37
	s_nop 0
	global_load_lds_dwordx4 v[224:225], off
	s_waitcnt vmcnt(8)
	s_waitcnt lgkmcnt(0)
	s_barrier
	s_setprio 1
	v_mfma_f32_16x16x32_bf16 v[116:119], v[144:147], v[184:187], v[116:119]
	v_mfma_f32_16x16x32_bf16 v[112:115], v[158:161], v[184:187], v[112:115]
	v_mfma_f32_16x16x32_bf16 v[100:103], v[144:147], v[192:195], v[100:103]
	v_mfma_f32_16x16x32_bf16 v[96:99], v[158:161], v[192:195], v[96:99]
	v_mfma_f32_16x16x32_bf16 v[84:87], v[144:147], v[200:203], v[84:87]
	v_mfma_f32_16x16x32_bf16 v[80:83], v[158:161], v[200:203], v[80:83]
	v_mfma_f32_16x16x32_bf16 v[68:71], v[144:147], v[208:211], v[68:71]
	v_mfma_f32_16x16x32_bf16 v[64:67], v[158:161], v[208:211], v[64:67]
	v_mfma_f32_16x16x32_bf16 v[116:119], v[154:157], v[188:191], v[116:119]
	v_mfma_f32_16x16x32_bf16 v[112:115], v[162:165], v[188:191], v[112:115]
	v_mfma_f32_16x16x32_bf16 v[100:103], v[154:157], v[196:199], v[100:103]
	v_mfma_f32_16x16x32_bf16 v[96:99], v[162:165], v[196:199], v[96:99]
	v_mfma_f32_16x16x32_bf16 v[84:87], v[154:157], v[204:207], v[84:87]
	v_mfma_f32_16x16x32_bf16 v[80:83], v[162:165], v[204:207], v[80:83]
	v_mfma_f32_16x16x32_bf16 v[68:71], v[154:157], v[212:215], v[68:71]
	v_mfma_f32_16x16x32_bf16 v[64:67], v[162:165], v[212:215], v[64:67]
	v_mfma_f32_16x16x32_bf16 v[124:127], v[168:171], v[184:187], v[124:127]
	v_mfma_f32_16x16x32_bf16 v[120:123], v[176:179], v[184:187], v[120:123]
	v_mfma_f32_16x16x32_bf16 v[108:111], v[168:171], v[192:195], v[108:111]
	v_mfma_f32_16x16x32_bf16 v[104:107], v[176:179], v[192:195], v[104:107]
	v_mfma_f32_16x16x32_bf16 v[92:95], v[168:171], v[200:203], v[92:95]
	v_mfma_f32_16x16x32_bf16 v[88:91], v[176:179], v[200:203], v[88:91]
	v_mfma_f32_16x16x32_bf16 v[76:79], v[168:171], v[208:211], v[76:79]
	v_mfma_f32_16x16x32_bf16 v[72:75], v[176:179], v[208:211], v[72:75]
	v_mfma_f32_16x16x32_bf16 v[124:127], v[172:175], v[188:191], v[124:127]
	v_mfma_f32_16x16x32_bf16 v[120:123], v[180:183], v[188:191], v[120:123]
	v_mfma_f32_16x16x32_bf16 v[108:111], v[172:175], v[196:199], v[108:111]
	v_mfma_f32_16x16x32_bf16 v[104:107], v[180:183], v[196:199], v[104:107]
	v_mfma_f32_16x16x32_bf16 v[92:95], v[172:175], v[204:207], v[92:95]
	v_mfma_f32_16x16x32_bf16 v[88:91], v[180:183], v[204:207], v[88:91]
	v_mfma_f32_16x16x32_bf16 v[76:79], v[172:175], v[212:215], v[76:79]
	v_mfma_f32_16x16x32_bf16 v[72:75], v[180:183], v[212:215], v[72:75]
	s_setprio 0
	s_barrier
; #define PG8_STAGE(bufoff, gbase, voff) do { _Pragma("unroll") for (int _i = 0; _i < 2; ++_i) \
;         __builtin_amdgcn_global_load_lds((const unsigned*)((const char*)(gbase) + (voff)[_i]), (PG8_LAS unsigned*)(lds + (bufoff) + ldsw + _i * 8192), 16, 0, 0); } while (0)
; #define PG8_LDA(dst, b, h) do { _Pragma("unroll") for (int m = 0; m < 4; ++m) _Pragma("unroll") for (int k = 0; k < 2; ++k) dst[m][k] = *(const PG8_LAS bf16x8*)(lds + PG8_SA(b, h) + aoff + m * 2048 + k * 1024); } while (0)
; #define PG8_MMA(ai, bj, At, Bt) do { __builtin_amdgcn_s_setprio(1); _Pragma("unroll") for (int m = 0; m < 4; ++m) _Pragma("unroll") for (int n = 0; n < 2; ++n) _Pragma("unroll") for (int k = 0; k < 2; ++k) \
;         acc[ai][bj][m][n] = __builtin_amdgcn_mfma_f32_16x16x32_bf16(Bt[n][k], At[m][k], acc[ai][bj][m][n], 0, 0, 0); __builtin_amdgcn_s_setprio(0); } while (0)
; #define PG8_WAIT_V(n) asm volatile("s_waitcnt vmcnt(" #n ")" ::: "memory")
; #define PG8_WAIT_L(n) asm volatile("s_waitcnt lgkmcnt(" #n ")" ::: "memory")
; #define PG8_BAR __builtin_amdgcn_s_barrier()
; #define PG8_SCHED __builtin_amdgcn_sched_barrier(0)
; template <class Epi, class Sched, bool ALIGN_EPI = false, bool SP2 = false>
; __device__ __forceinline__ void gemm_phase(PG8_LAS unsigned char* lds, const Gemm g, const Sched& S, const Epi& E) {
;     ...
;         for (int t = 0; t < nt; t += 2) {
;     ...
;             PG8_LDA(At, 1, 1); PG8_STAGE(PG8_SB(1, 0), b3, voffB); PG8_STAGE(PG8_SB(1, 1), b3 + hstepB, voffB); PG8_STAGE(PG8_SA(1, 0), a3, voffA);
;             PG8_WAIT_V(8); PG8_WAIT_L(0); PG8_BAR; PG8_MMA(1, 0, At, B0); PG8_MMA(1, 1, At, B1); PG8_BAR; PG8_SCHED;
	s_add_i32 s4, s59, s47
	v_lshl_add_u64 v[216:217], v[216:217], 0, s[14:15]
	s_mov_b32 m0, s4
	ds_read_b128 v[184:187], v151 offset:49152
	ds_read_b128 v[188:191], v151 offset:50176
	ds_read_b128 v[192:195], v151 offset:51200
	ds_read_b128 v[196:199], v151 offset:52224
	ds_read_b128 v[200:203], v151 offset:53248
	ds_read_b128 v[204:207], v151 offset:54272
	ds_read_b128 v[208:211], v151 offset:55296
	ds_read_b128 v[212:215], v151 offset:56320
	global_load_lds_dwordx4 v[216:217], off
	s_add_i32 m0, s4, 0x2000
	s_add_u32 s4, s30, 0x80080
	v_lshl_add_u64 v[216:217], v[218:219], 0, s[14:15]
	s_addc_u32 s5, s31, 0
	s_add_i32 s30, s60, s47
	global_load_lds_dwordx4 v[216:217], off
	v_lshl_add_u64 v[216:217], s[4:5], 0, v[132:133]
	s_mov_b32 m0, s30
	s_nop 0
	global_load_lds_dwordx4 v[216:217], off
	v_lshl_add_u64 v[216:217], s[4:5], 0, v[128:129]
	s_add_i32 m0, s30, 0x2000
	s_nop 0
	global_load_lds_dwordx4 v[216:217], off
	v_lshl_add_u64 v[216:217], v[220:221], 0, s[14:15]
	s_mov_b32 m0, s39
	s_nop 0
	global_load_lds_dwordx4 v[216:217], off
	v_lshl_add_u64 v[216:217], v[222:223], 0, s[14:15]
	s_mov_b32 m0, s40
	s_nop 0
	global_load_lds_dwordx4 v[216:217], off
	s_waitcnt vmcnt(8)
	s_waitcnt lgkmcnt(0)
	s_barrier
	s_setprio 1
	v_mfma_f32_16x16x32_bf16 v[52:55], v[144:147], v[184:187], v[52:55]
	v_mfma_f32_16x16x32_bf16 v[48:51], v[158:161], v[184:187], v[48:51]
	v_mfma_f32_16x16x32_bf16 v[36:39], v[144:147], v[192:195], v[36:39]
	v_mfma_f32_16x16x32_bf16 v[32:35], v[158:161], v[192:195], v[32:35]
	v_mfma_f32_16x16x32_bf16 v[20:23], v[144:147], v[200:203], v[20:23]
	v_mfma_f32_16x16x32_bf16 v[16:19], v[158:161], v[200:203], v[16:19]
	v_mfma_f32_16x16x32_bf16 v[8:11], v[144:147], v[208:211], v[8:11]
	v_mfma_f32_16x16x32_bf16 v[4:7], v[158:161], v[208:211], v[4:7]
	v_mfma_f32_16x16x32_bf16 v[52:55], v[154:157], v[188:191], v[52:55]
	v_mfma_f32_16x16x32_bf16 v[48:51], v[162:165], v[188:191], v[48:51]
	v_mfma_f32_16x16x32_bf16 v[36:39], v[154:157], v[196:199], v[36:39]
	v_mfma_f32_16x16x32_bf16 v[32:35], v[162:165], v[196:199], v[32:35]
	v_mfma_f32_16x16x32_bf16 v[20:23], v[154:157], v[204:207], v[20:23]
	v_mfma_f32_16x16x32_bf16 v[16:19], v[162:165], v[204:207], v[16:19]
	v_mfma_f32_16x16x32_bf16 v[8:11], v[154:157], v[212:215], v[8:11]
	v_mfma_f32_16x16x32_bf16 v[4:7], v[162:165], v[212:215], v[4:7]
	v_mfma_f32_16x16x32_bf16 v[60:63], v[168:171], v[184:187], v[60:63]
	v_mfma_f32_16x16x32_bf16 v[56:59], v[176:179], v[184:187], v[56:59]
	v_mfma_f32_16x16x32_bf16 v[44:47], v[168:171], v[192:195], v[44:47]
	v_mfma_f32_16x16x32_bf16 v[40:43], v[176:179], v[192:195], v[40:43]
	v_mfma_f32_16x16x32_bf16 v[28:31], v[168:171], v[200:203], v[28:31]
	v_mfma_f32_16x16x32_bf16 v[24:27], v[176:179], v[200:203], v[24:27]
	v_mfma_f32_16x16x32_bf16 v[12:15], v[168:171], v[208:211], v[12:15]
	v_mfma_f32_16x16x32_bf16 v[0:3], v[176:179], v[208:211], v[0:3]
	v_mfma_f32_16x16x32_bf16 v[60:63], v[172:175], v[188:191], v[60:63]
	v_mfma_f32_16x16x32_bf16 v[56:59], v[180:183], v[188:191], v[56:59]
	v_mfma_f32_16x16x32_bf16 v[44:47], v[172:175], v[196:199], v[44:47]
	v_mfma_f32_16x16x32_bf16 v[40:43], v[180:183], v[196:199], v[40:43]
	v_mfma_f32_16x16x32_bf16 v[28:31], v[172:175], v[204:207], v[28:31]
	v_mfma_f32_16x16x32_bf16 v[24:27], v[180:183], v[204:207], v[24:27]
	v_mfma_f32_16x16x32_bf16 v[12:15], v[172:175], v[212:215], v[12:15]
	v_mfma_f32_16x16x32_bf16 v[0:3], v[180:183], v[212:215], v[0:3]
	s_add_i32 s58, s58, 2
	s_add_u32 s28, s28, 0x100
	s_addc_u32 s29, s29, 0
	s_add_u32 s56, s56, 0x100
	s_addc_u32 s57, s57, 0
	s_cmp_gt_u32 s58, 29
	s_setprio 0
	s_barrier
	s_cbranch_scc0 .LBB0_1287
	s_and_b64 vcc, exec, s[48:49]
	s_cbranch_vccz .LBB0_1290
	s_barrier
